# HB residual plane also in 16x32 sub-tile order (EpiResid loads/stores, GEMM1 A fills 1 KiB contiguous; prologue and final norm remapped) on top of tiled ACT + saddr DMA
# speedup vs baseline: 1.0122x; 1.0076x over previous
.LBB0_121:
	v_mov_b32_e32 v1, v0
	s_cmpk_gt_i32 s12, 0x1fff
	s_cbranch_scc1 .LBB0_126
	s_waitcnt vmcnt(13)
	v_and_b32_e32 v10, 63, v1
	v_lshrrev_b32_e32 v91, 3, v10
	v_lshlrev_b32_e32 v91, 10, v91
	v_and_b32_e32 v92, 7, v10
	v_lshl_or_b32 v91, v92, 3, v91
	v_mbcnt_lo_u32_b32 v1, -1, 0
	v_mbcnt_hi_u32_b32 v2, -1, v1
	v_and_b32_e32 v1, 64, v2
	v_add_u32_e32 v3, 64, v1
	v_xor_b32_e32 v1, 1, v2
	v_cmp_lt_i32_e32 vcc, v1, v3
	v_xor_b32_e32 v4, 2, v2
	s_ashr_i32 s13, s12, 31
	v_cndmask_b32_e32 v1, v2, v1, vcc
	v_cmp_lt_i32_e32 vcc, v4, v3
	s_lshl_b64 s[2:3], s[12:13], 7
	s_ashr_i32 s15, s14, 31
	v_cndmask_b32_e32 v4, v2, v4, vcc
	v_lshlrev_b32_e32 v12, 2, v4
	v_xor_b32_e32 v4, 4, v2
	v_cmp_lt_i32_e32 vcc, v4, v3
	s_lshl_b64 s[4:5], s[12:13], 12
	v_lshl_or_b32 v8, v10, 3, s4
	v_cndmask_b32_e32 v4, v2, v4, vcc
	v_lshlrev_b32_e32 v13, 2, v4
	v_xor_b32_e32 v4, 8, v2
	v_cmp_lt_i32_e32 vcc, v4, v3
	v_mov_b32_e32 v9, s5
	s_lshl_b64 s[16:17], s[14:15], 12
	v_cndmask_b32_e32 v4, v2, v4, vcc
	s_waitcnt vmcnt(12)
	v_lshlrev_b32_e32 v14, 2, v4
	v_xor_b32_e32 v4, 16, v2
	v_cmp_lt_i32_e32 vcc, v4, v3
	s_lshl_b64 s[4:5], s[12:13], 13
	v_readlane_b32 s36, v252, 25
	v_cndmask_b32_e32 v4, v2, v4, vcc
	v_lshlrev_b32_e32 v15, 2, v4
	v_xor_b32_e32 v4, 32, v2
	v_cmp_lt_i32_e32 vcc, v4, v3
	v_mov_b32_e32 v3, 0
	v_readlane_b32 s37, v252, 26
	v_cndmask_b32_e32 v2, v2, v4, vcc
	v_lshlrev_b32_e32 v16, 2, v2
	v_lshlrev_b32_e32 v2, 2, v10
	v_lshl_add_u64 v[4:5], s[2:3], 0, v[2:3]
	s_mov_b64 s[2:3], 0x100000
	v_lshl_add_u64 v[6:7], v[4:5], 0, s[2:3]
	s_lshl_b64 s[2:3], s[14:15], 7
	s_add_u32 s4, s36, s4
	v_lshlrev_b32_e32 v2, 4, v10
	s_addc_u32 s5, s37, s5
	v_lshl_add_u64 v[2:3], s[4:5], 0, v[2:3]
	s_mov_b64 s[4:5], 0x1000
	v_lshlrev_b32_e32 v1, 2, v1
	v_cmp_gt_u32_e32 vcc, 32, v10
	v_cmp_eq_u32_e64 s[0:1], 0, v10
	v_lshl_add_u64 v[10:11], v[2:3], 0, s[4:5]
	s_lshl_b64 s[18:19], s[14:15], 13
	s_movk_i32 s13, 0x7fff
	s_mov_b32 s15, 0xffff0000
	s_mov_b32 s20, 0x4200000
	v_readlane_b32 s38, v252, 27
	v_readlane_b32 s39, v252, 28
	v_readlane_b32 s40, v252, 29
	v_readlane_b32 s41, v252, 30
	v_readlane_b32 s42, v252, 31
	v_readlane_b32 s43, v252, 32
	v_readlane_b32 s44, v252, 33
	v_readlane_b32 s45, v252, 34
	v_readlane_b32 s46, v252, 35
	v_readlane_b32 s47, v252, 36
	v_readlane_b32 s48, v252, 37
	v_readlane_b32 s49, v252, 38
	v_readlane_b32 s50, v252, 39
	v_readlane_b32 s51, v252, 40
	s_branch .LBB0_124

.LBB0_124:
	s_waitcnt lgkmcnt(0)
	global_load_dwordx4 v[18:21], v[10:11], off offset:-4096
	global_load_dwordx4 v[22:25], v[10:11], off offset:-3072
	global_load_dwordx4 v[26:29], v[10:11], off offset:-2048
	global_load_dwordx4 v[30:33], v[10:11], off offset:-1024
	global_load_dwordx4 v[34:37], v[10:11], off
	global_load_dwordx4 v[38:41], v[10:11], off offset:1024
	global_load_dwordx4 v[42:45], v[10:11], off offset:2048
	global_load_dwordx4 v[2:5], v[10:11], off offset:3072
	v_readlane_b32 s36, v252, 5
	v_readlane_b32 s50, v252, 19
	v_readlane_b32 s51, v252, 20
	v_readlane_b32 s37, v252, 6
	v_readlane_b32 s38, v252, 7
	s_waitcnt vmcnt(12)
	s_lshr_b32 s98, s12, 4
	s_lshl_b32 s98, s98, 16
	s_and_b32 s99, s12, 15
	s_lshl_b32 s99, s99, 6
	s_add_u32 s98, s98, s99
	s_add_u32 s98, s98, s20
	s_lshl_b32 s100, s12, 2
	s_and_b32 s100, s100, 32
	s_add_u32 s98, s50, s98
	s_addc_u32 s99, s51, 0
	v_xor_b32_e32 v90, s100, v91
	v_readlane_b32 s39, v252, 8
	s_nop 0
	v_readlane_b32 s40, v252, 9
	v_readlane_b32 s41, v252, 10
	v_readlane_b32 s42, v252, 11
	v_readlane_b32 s43, v252, 12
	v_readlane_b32 s44, v252, 13
	v_readlane_b32 s45, v252, 14
	v_readlane_b32 s46, v252, 15
	v_readlane_b32 s47, v252, 16
	v_readlane_b32 s48, v252, 17
	v_readlane_b32 s49, v252, 18
	s_waitcnt vmcnt(7)
	v_mul_f32_e32 v17, v19, v19
	v_mul_f32_e32 v48, v21, v21
	s_waitcnt vmcnt(6)
	v_mul_f32_e32 v49, v23, v23
	v_mul_f32_e32 v50, v25, v25
	s_waitcnt vmcnt(5)
	v_mul_f32_e32 v51, v27, v27
	v_mul_f32_e32 v52, v29, v29
	v_fmac_f32_e32 v17, v18, v18
	v_fmac_f32_e32 v48, v20, v20
	v_fmac_f32_e32 v49, v22, v22
	v_fmac_f32_e32 v50, v24, v24
	s_waitcnt vmcnt(4)
	v_mul_f32_e32 v53, v31, v31
	v_mul_f32_e32 v54, v33, v33
	v_fmac_f32_e32 v51, v26, v26
	v_fmac_f32_e32 v52, v28, v28
	v_add_f32_e32 v17, v17, v48
	v_add_f32_e32 v48, v49, v50
	s_waitcnt vmcnt(3)
	v_mul_f32_e32 v55, v35, v35
	v_mul_f32_e32 v56, v37, v37
	v_fmac_f32_e32 v53, v30, v30
	v_fmac_f32_e32 v54, v32, v32
	v_add_f32_e32 v49, v51, v52
	v_add_f32_e32 v17, v17, v48
	s_waitcnt vmcnt(2)
	v_mul_f32_e32 v57, v39, v39
	v_mul_f32_e32 v58, v41, v41
	v_fmac_f32_e32 v55, v34, v34
	v_fmac_f32_e32 v56, v36, v36
	v_add_f32_e32 v50, v53, v54
	v_add_f32_e32 v17, v17, v49
	s_waitcnt vmcnt(1)
	v_mul_f32_e32 v59, v43, v43
	v_mul_f32_e32 v60, v45, v45
	v_fmac_f32_e32 v57, v38, v38
	v_fmac_f32_e32 v58, v40, v40
	v_add_f32_e32 v51, v55, v56
	v_add_f32_e32 v17, v17, v50
	s_waitcnt vmcnt(0)
	v_mul_f32_e32 v61, v3, v3
	v_mul_f32_e32 v62, v5, v5
	v_fmac_f32_e32 v59, v42, v42
	v_fmac_f32_e32 v60, v44, v44
	v_add_f32_e32 v52, v57, v58
	v_add_f32_e32 v17, v17, v51
	v_fmac_f32_e32 v61, v2, v2
	v_fmac_f32_e32 v62, v4, v4
	v_add_f32_e32 v53, v59, v60
	v_add_f32_e32 v17, v17, v52
	v_add_f32_e32 v54, v61, v62
	v_add_f32_e32 v17, v17, v53
	v_add_f32_e32 v17, v17, v54
	ds_bpermute_b32 v48, v1, v17
	v_bfe_u32 v63, v18, 16, 1
	v_bfe_u32 v65, v20, 16, 1
	v_bfe_u32 v64, v19, 16, 1
	v_bfe_u32 v66, v21, 16, 1
	s_waitcnt lgkmcnt(0)
	v_add_f32_e32 v17, v17, v48
	ds_bpermute_b32 v48, v12, v17
	v_bfe_u32 v67, v22, 16, 1
	v_bfe_u32 v69, v24, 16, 1
	v_bfe_u32 v71, v26, 16, 1
	v_bfe_u32 v73, v28, 16, 1
	v_add3_u32 v18, v18, v63, s13
	v_add3_u32 v20, v20, v65, s13
	v_bfe_u32 v68, v23, 16, 1
	v_bfe_u32 v70, v25, 16, 1
	v_bfe_u32 v72, v27, 16, 1
	v_bfe_u32 v74, v29, 16, 1
	v_add3_u32 v19, v19, v64, s13
	v_add3_u32 v21, v21, v66, s13
	v_add3_u32 v22, v22, v67, s13
	v_add3_u32 v24, v24, v69, s13
	v_add3_u32 v26, v26, v71, s13
	v_add3_u32 v28, v28, v73, s13
	v_lshrrev_b32_e32 v18, 16, v18
	v_lshrrev_b32_e32 v20, 16, v20
	v_add3_u32 v23, v23, v68, s13
	v_add3_u32 v25, v25, v70, s13
	v_add3_u32 v27, v27, v72, s13
	v_add3_u32 v29, v29, v74, s13
	v_lshrrev_b32_e32 v22, 16, v22
	v_lshrrev_b32_e32 v24, 16, v24
	v_lshrrev_b32_e32 v26, 16, v26
	v_lshrrev_b32_e32 v28, 16, v28
	v_and_or_b32 v18, v19, s15, v18
	v_and_or_b32 v19, v21, s15, v20
	v_and_or_b32 v20, v23, s15, v22
	v_and_or_b32 v21, v25, s15, v24
	v_and_or_b32 v22, v27, s15, v26
	v_and_or_b32 v23, v29, s15, v28
	global_store_dwordx2 v90, v[18:19], s[98:99]
	v_add_u32_e32 v92, 0x2000, v90
	global_store_dwordx2 v92, v[20:21], s[98:99]
	v_add_u32_e32 v92, 0x4000, v90
	global_store_dwordx2 v92, v[22:23], s[98:99]
	v_bfe_u32 v19, v34, 16, 1
	s_waitcnt lgkmcnt(0)
	v_add_f32_e32 v17, v17, v48
	v_add3_u32 v19, v34, v19, s13
	v_bfe_u32 v20, v35, 16, 1
	ds_bpermute_b32 v48, v13, v17
	v_lshrrev_b32_e32 v19, 16, v19
	v_add3_u32 v20, v35, v20, s13
	v_and_or_b32 v20, v20, s15, v19
	v_bfe_u32 v19, v36, 16, 1
	v_add3_u32 v19, v36, v19, s13
	v_bfe_u32 v21, v37, 16, 1
	v_lshrrev_b32_e32 v19, 16, v19
	v_add3_u32 v21, v37, v21, s13
	v_and_or_b32 v21, v21, s15, v19
	v_bfe_u32 v19, v38, 16, 1
	s_waitcnt lgkmcnt(0)
	v_add_f32_e32 v17, v17, v48
	v_add_u32_e32 v92, 0x8000, v90
	global_store_dwordx2 v92, v[20:21], s[98:99]
	v_add3_u32 v19, v38, v19, s13
	v_bfe_u32 v20, v39, 16, 1
	ds_bpermute_b32 v48, v14, v17
	v_lshrrev_b32_e32 v19, 16, v19
	v_add3_u32 v20, v39, v20, s13
	v_and_or_b32 v20, v20, s15, v19
	v_bfe_u32 v19, v40, 16, 1
	v_add3_u32 v19, v40, v19, s13
	v_bfe_u32 v21, v41, 16, 1
	v_lshrrev_b32_e32 v19, 16, v19
	v_add3_u32 v21, v41, v21, s13
	v_and_or_b32 v21, v21, s15, v19
	v_bfe_u32 v19, v42, 16, 1
	s_waitcnt lgkmcnt(0)
	v_add_f32_e32 v17, v17, v48
	v_add_u32_e32 v92, 0xa000, v90
	global_store_dwordx2 v92, v[20:21], s[98:99]
	v_add3_u32 v19, v42, v19, s13
	v_bfe_u32 v20, v43, 16, 1
	ds_bpermute_b32 v25, v15, v17
	v_lshrrev_b32_e32 v19, 16, v19
	v_add3_u32 v20, v43, v20, s13
	v_and_or_b32 v20, v20, s15, v19
	v_bfe_u32 v19, v44, 16, 1
	v_add3_u32 v19, v44, v19, s13
	v_bfe_u32 v21, v45, 16, 1
	v_lshrrev_b32_e32 v19, 16, v19
	v_add3_u32 v21, v45, v21, s13
	v_and_or_b32 v21, v21, s15, v19
	v_bfe_u32 v19, v2, 16, 1
	s_waitcnt lgkmcnt(0)
	v_add_f32_e32 v17, v17, v25
	v_add3_u32 v2, v2, v19, s13
	v_bfe_u32 v19, v3, 16, 1
	ds_bpermute_b32 v18, v16, v17
	v_lshrrev_b32_e32 v2, 16, v2
	v_add3_u32 v3, v3, v19, s13
	v_bfe_u32 v75, v30, 16, 1
	v_bfe_u32 v77, v32, 16, 1
	v_and_or_b32 v2, v3, s15, v2
	v_bfe_u32 v3, v4, 16, 1
	v_bfe_u32 v76, v31, 16, 1
	v_bfe_u32 v78, v33, 16, 1
	v_add3_u32 v30, v30, v75, s13
	v_add3_u32 v32, v32, v77, s13
	v_add3_u32 v3, v4, v3, s13
	v_bfe_u32 v4, v5, 16, 1
	v_add3_u32 v31, v31, v76, s13
	v_add3_u32 v33, v33, v78, s13
	v_lshrrev_b32_e32 v30, 16, v30
	v_lshrrev_b32_e32 v32, 16, v32
	v_lshrrev_b32_e32 v3, 16, v3
	v_add3_u32 v4, v5, v4, s13
	v_and_or_b32 v24, v31, s15, v30
	v_and_or_b32 v25, v33, s15, v32
	v_and_or_b32 v3, v4, s15, v3
	v_add_u32_e32 v92, 0x6000, v90
	global_store_dwordx2 v92, v[24:25], s[98:99]
	v_add_u32_e32 v92, 0xc000, v90
	global_store_dwordx2 v92, v[20:21], s[98:99]
	v_add_u32_e32 v92, 0xe000, v90
	global_store_dwordx2 v92, v[2:3], s[98:99]
	s_and_saveexec_b64 s[4:5], vcc
	s_cbranch_execz .LBB0_123
	v_readlane_b32 s36, v252, 5
	s_waitcnt lgkmcnt(0)
	v_add_f32_e32 v2, v17, v18
	v_readlane_b32 s50, v252, 19
	v_readlane_b32 s51, v252, 20
	v_cndmask_b32_e64 v4, 0, v2, s[0:1]
	v_readlane_b32 s37, v252, 6
	v_lshl_add_u64 v[2:3], s[50:51], 0, v[6:7]
	v_readlane_b32 s38, v252, 7
	v_readlane_b32 s39, v252, 8
	v_readlane_b32 s40, v252, 9
	v_readlane_b32 s41, v252, 10
	v_readlane_b32 s42, v252, 11
	v_readlane_b32 s43, v252, 12
	v_readlane_b32 s44, v252, 13
	v_readlane_b32 s45, v252, 14
	v_readlane_b32 s46, v252, 15
	v_readlane_b32 s47, v252, 16
	v_readlane_b32 s48, v252, 17
	v_readlane_b32 s49, v252, 18
	global_store_dword v[2:3], v4, off
	s_branch .LBB0_123

.LBB0_243:
	v_readlane_b32 s0, v255, 11
	v_readlane_b32 s3, v255, 14
	s_lshl_b32 s0, s0, 1
	s_ashr_i32 s7, s3, 1
	s_add_i32 s7, s7, s0
	v_readlane_b32 s0, v252, 60
	v_readlane_b32 s1, v252, 61
	s_andn2_b64 vcc, exec, s[0:1]
	v_readfirstlane_b32 s2, v210
	s_cbranch_vccnz .LBB0_269
	v_lshlrev_b32_e32 v2, 4, v210
	s_waitcnt vmcnt(15)
	v_add_u32_e32 v20, 0x2000, v2
	v_ashrrev_i32_e32 v21, 31, v20
	v_lshrrev_b32_e32 v21, 22, v21
	v_add_u32_e32 v21, v20, v21
	s_waitcnt vmcnt(10)
	v_ashrrev_i32_e32 v24, 10, v21
	v_mul_i32_i24_e32 v21, 0x400, v24
	v_sub_u32_e32 v20, v20, v21
	v_lshrrev_b32_e32 v21, 4, v20
	v_bitop3_b32 v20, v21, v20, 32 bitop3:0x6c
	v_ashrrev_i32_e32 v21, 31, v20
	v_lshrrev_b32_e32 v21, 26, v21
	s_ashr_i32 s3, s2, 6
	v_add_u32_e32 v21, v20, v21
	v_lshlrev_b32_e32 v22, 3, v24
	s_lshl_b32 s28, s3, 10
	s_mul_i32 s1, s7, 0x4200000
	v_readlane_b32 s6, v252, 58
	v_ashrrev_i32_e32 v25, 6, v21
	v_and_b32_e32 v22, -16, v22
	s_mul_hi_i32 s0, s7, 0x4200000
	s_add_u32 s29, s6, s1
	v_readlane_b32 s1, v252, 59
	v_add_u32_e32 v22, v25, v22
	s_addc_u32 s38, s1, s0
	v_and_b32_e32 v23, 3, v25
	s_mov_b32 s0, 0xfffe0
	s_waitcnt vmcnt(9)
	v_lshrrev_b32_e32 v26, 2, v22
	v_lshlrev_b32_e32 v27, 1, v22
	v_and_b32_e32 v21, 0xc0, v21
	v_and_or_b32 v23, v22, s0, v23
	v_and_b32_e32 v26, 4, v26
	v_and_b32_e32 v27, 24, v27
	v_sub_u32_e32 v20, v20, v21
	s_waitcnt vmcnt(8)
	v_mov_b32_e32 v30, 1
	v_or3_b32 v23, v23, v26, v27
	v_lshlrev_b32_e32 v26, 5, v24
	v_ashrrev_i16_sdwa v20, v30, sext(v20) dst_sel:DWORD dst_unused:UNUSED_PAD src0_sel:DWORD src1_sel:BYTE_0
	v_and_b32_e32 v27, 32, v26
	v_bfe_i32 v26, v20, 0, 16
	v_add_lshl_u32 v20, v27, v26, 1
	v_lshl_add_u32 v156, v23, 12, v20
	v_lshl_add_u32 v158, v22, 12, v20
	v_bfe_i32 v20, v210, 27, 1
	v_lshrrev_b32_e32 v20, 22, v20
	v_add_u32_e32 v20, v2, v20
	v_and_b32_e32 v20, 0xfffffc00, v20
	v_sub_u32_e32 v2, v2, v20
	v_lshrrev_b32_e32 v20, 4, v2
	v_ashrrev_i32_e32 v21, 31, v210
	v_bitop3_b32 v2, v20, v2, 32 bitop3:0x6c
	v_lshrrev_b32_e32 v21, 26, v21
	v_ashrrev_i32_e32 v20, 31, v2
	v_add_u32_e32 v21, v210, v21
	v_lshrrev_b32_e32 v20, 26, v20
	v_ashrrev_i32_e32 v28, 6, v21
	v_add_u32_e32 v20, v2, v20
	v_lshlrev_b32_e32 v21, 3, v28
	v_ashrrev_i32_e32 v27, 6, v20
	v_and_b32_e32 v21, -16, v21
	v_add_u32_e32 v21, v27, v21
	v_and_b32_e32 v22, 3, v27
	v_lshrrev_b32_e32 v23, 2, v21
	v_lshlrev_b32_e32 v29, 1, v21
	v_and_b32_e32 v20, 0xc0, v20
	v_and_or_b32 v22, v21, s0, v22
	v_and_b32_e32 v23, 4, v23
	v_and_b32_e32 v29, 24, v29
	v_sub_u32_e32 v2, v2, v20
	v_or3_b32 v22, v22, v23, v29
	v_lshlrev_b32_e32 v23, 5, v28
	v_ashrrev_i16_sdwa v2, v30, sext(v2) dst_sel:DWORD dst_unused:UNUSED_PAD src0_sel:DWORD src1_sel:BYTE_0
	v_readlane_b32 s0, v254, 35
	v_and_b32_e32 v23, 32, v23
	v_bfe_i32 v29, v2, 0, 16
	v_readlane_b32 s1, v254, 36
	s_add_u32 s22, s29, s0
	v_add_lshl_u32 v20, v23, v29, 1
	s_addc_u32 s23, s38, s1
	s_add_i32 s39, s28, 0
	v_lshl_add_u32 v2, v22, 12, v20
	s_add_i32 m0, s39, 0x10000
	v_lshl_add_u32 v160, v21, 12, v20
	v_lshrrev_b32_e32 v160, 7, v210
	v_lshlrev_b32_e32 v160, 16, v160
	v_bfe_u32 v248, v210, 6, 1
	v_lshl_or_b32 v160, v248, 10, v160
	v_and_b32_e32 v248, 63, v210
	v_lshl_or_b32 v160, v248, 4, v160
	v_add_u32_e32 v158, 0x40000, v160
	s_movk_i32 s100, 0x800
	s_mov_b32 s101, 0
	global_load_lds_dwordx4 v2, s[22:23]
	s_add_i32 m0, s39, 0x12000
	s_add_u32 s0, s22, 0x80000
	global_load_lds_dwordx4 v156, s[22:23]
	s_addc_u32 s1, s23, 0
	s_add_i32 m0, s39, 0x14000
	s_add_i32 s41, s39, 0x2000
	global_load_lds_dwordx4 v2, s[0:1]
	s_add_i32 m0, s39, 0x16000
	s_add_i32 s42, s39, 0x4000
	global_load_lds_dwordx4 v156, s[0:1]
	v_readlane_b32 s0, v254, 41
	s_mov_b32 m0, s39
	v_readlane_b32 s1, v254, 42
	s_add_i32 s43, s39, 0x6000
	s_andn2_b64 vcc, exec, s[4:5]
	s_nop 2
	global_load_lds_dwordx4 v160, s[0:1]
	s_mov_b32 m0, s41
	s_nop 0
	global_load_lds_dwordx4 v158, s[0:1]
	v_readlane_b32 s0, v254, 43
	s_mov_b32 m0, s42
	v_readlane_b32 s1, v254, 44
	s_nop 4
	global_load_lds_dwordx4 v160, s[0:1]
	s_mov_b32 m0, s43
	s_nop 0
	global_load_lds_dwordx4 v158, s[0:1]
	s_cbranch_vccnz .LBB0_248
	s_waitcnt vmcnt(0)
	v_add_f32_e32 v20, v16, v17
	v_add_f32_e32 v21, v18, v19
	v_add_f32_e32 v20, v20, v21
	v_add_f32_e32 v21, v12, v13
	v_add_f32_e32 v22, v14, v15
	v_add_f32_e32 v20, 0, v20
	v_add_f32_e32 v21, v21, v22
	v_add_f32_e32 v20, v20, v21
	v_add_f32_e32 v21, v8, v9
	v_add_f32_e32 v22, v10, v11
	v_add_f32_e32 v21, v21, v22
	v_add_f32_e32 v20, v20, v21
	v_add_f32_e32 v21, v4, v5
	v_add_f32_e32 v22, v6, v7
	v_add_f32_e32 v21, v21, v22
	v_and_b32_e32 v22, 64, v208
	v_add_f32_e32 v20, v20, v21
	v_xor_b32_e32 v21, 1, v208
	v_add_u32_e32 v22, 64, v22
	v_cmp_lt_i32_e32 vcc, v21, v22
	v_and_b32_e32 v22, 1, v210
	s_nop 0
	v_cndmask_b32_e32 v21, v208, v21, vcc
	v_lshlrev_b32_e32 v21, 2, v21
	ds_bpermute_b32 v21, v21, v20
	v_cmp_eq_u32_e32 vcc, 0, v22
	s_and_saveexec_b64 s[0:1], vcc
	s_cbranch_execz .LBB0_247
	s_waitcnt lgkmcnt(0)
	v_add_f32_e32 v20, v20, v21
	v_fmamk_f32 v20, v20, 0x3a000000, v1
	v_rsq_f32_e32 v20, v20
	v_lshl_add_u32 v21, v210, 1, 0
	v_add_u32_e32 v21, 0x21000, v21
	ds_write_b32 v21, v20

.LBB0_250:
	s_waitcnt vmcnt(0)
	v_lshrrev_b32_e32 v35, 1, v210
	v_and_b32_e32 v35, 24, v35
	v_and_b32_e32 v34, 15, v210
	v_lshlrev_b32_e32 v36, 1, v35
	v_readlane_b32 s18, v254, 41
	v_lshl_or_b32 v190, s6, 6, v34
	v_lshl_or_b32 v36, v34, 6, v36
	v_lshlrev_b32_e32 v34, 2, v34
	s_lshl_b32 s3, s3, 5
	v_mov_b32_e32 v161, v3
	v_readlane_b32 s19, v254, 42
	s_lshl_b32 s8, s6, 13
	v_and_b32_e32 v37, 32, v34
	s_and_b32 s3, s3, 0x60
	s_add_i32 m0, s39, 0x18000
	v_lshl_add_u64 v[20:21], v[20:21], 0, s[30:31]
	v_lshl_add_u64 v[30:31], s[18:19], 0, v[160:161]
	v_mov_b32_e32 v159, v3
	v_bitop3_b32 v38, v36, s8, v37 bitop3:0xde
	s_lshl_b32 s8, s3, 7
	s_waitcnt vmcnt(2)
	s_barrier
	global_load_lds_dwordx4 v[20:21], off
	v_lshl_add_u64 v[20:21], v[22:23], 0, s[30:31]
	s_add_i32 m0, s39, 0x1a000
	s_add_i32 s44, s39, 0x8000
	s_add_i32 s45, s39, 0xa000
	v_lshl_add_u64 v[32:33], s[18:19], 0, v[158:159]
	v_bitop3_b32 v191, s8, v36, v37 bitop3:0xf6
	global_load_lds_dwordx4 v[20:21], off
	v_lshl_add_u64 v[20:21], v[30:31], 0, s[100:101]
	s_mov_b32 m0, s44
	s_add_u32 s8, s22, 0x80080
	global_load_lds_dwordx4 v[20:21], off
	v_lshl_add_u64 v[20:21], v[32:33], 0, s[100:101]
	s_mov_b32 m0, s45
	s_addc_u32 s9, s23, 0
	global_load_lds_dwordx4 v[20:21], off
	s_add_i32 m0, s39, 0x1c000
	v_lshl_add_u64 v[20:21], s[8:9], 0, v[2:3]
	global_load_lds_dwordx4 v[20:21], off
	v_lshl_add_u64 v[20:21], s[8:9], 0, v[156:157]
	s_add_i32 m0, s39, 0x1e000
	v_readlane_b32 s8, v252, 45
	global_load_lds_dwordx4 v[20:21], off
	v_lshlrev_b32_e32 v20, 2, v35
	v_mov_b32_e32 v21, v3
	v_readlane_b32 s9, v252, 46
	s_cmpk_lt_u32 s2, 0x100
	s_cselect_b64 s[12:13], -1, 0
	v_lshl_add_u64 v[162:163], s[8:9], 0, v[20:21]
	v_lshlrev_b32_e32 v20, 15, v28
	v_and_b32_e32 v20, 0xffff0000, v20
	v_lshl_add_u32 v20, v27, 12, v20
	v_and_b32_e32 v21, 1, v28
	s_lshl_b32 s2, s6, 8
	v_lshl_or_b32 v20, v21, 6, v20
	s_add_i32 s2, s2, 0
	v_lshl_add_u32 v168, v29, 1, v20
	v_lshlrev_b32_e32 v20, 15, v24
	s_add_i32 s2, s2, 0x21000
	v_and_b32_e32 v20, 0xffff0000, v20
	s_waitcnt vmcnt(6)
	v_add_u32_e32 v192, s2, v34
	v_or_b32_e32 v193, s3, v35
	v_lshl_add_u32 v20, v25, 12, v20
	v_and_b32_e32 v21, 1, v24
	v_readlane_b32 s2, v254, 37
	v_lshl_or_b32 v20, v21, 6, v20
	v_readlane_b32 s3, v254, 38
	v_mov_b32_e32 v169, v3
	v_lshl_add_u32 v170, v26, 1, v20
	v_mov_b32_e32 v168, v160
	v_mov_b32_e32 v170, v158
	v_mov_b32_e32 v171, v3
	s_mov_b32 s46, 0
	v_add_u32_e32 v194, 0, v38
	v_readlane_b32 s47, v254, 34
	s_mov_b32 s6, s2
	s_mov_b64 s[2:3], s[18:19]
	s_barrier
	s_branch .LBB0_253

.LBB0_255:
	s_ashr_i32 s17, s16, 31
	s_lshl_b64 s[8:9], s[16:17], 20
	v_readlane_b32 s18, v254, 39
	v_readlane_b32 s19, v254, 40
	s_add_u32 s18, s18, s8
	s_addc_u32 s19, s19, s9
	s_and_b64 s[8:9], s[36:37], exec
	s_cselect_b32 s8, s19, s3
	s_cselect_b32 s9, s18, s2
	s_ashr_i32 s15, s14, 31
	s_lshl_b64 s[20:21], s[14:15], 20
	s_add_u32 s20, s29, s20
	s_addc_u32 s21, s38, s21
	s_and_b64 s[26:27], s[36:37], exec
	s_cselect_b32 s15, s21, s23
	s_cselect_b32 s17, s20, s22
	s_add_u32 s2, s2, 0x80800
	s_addc_u32 s3, s3, 0
	s_add_u32 s33, s22, 0x100
	v_mov_b32_e32 v20, 0
	s_addc_u32 s34, s23, 0
	s_mov_b32 s35, -2
	v_mov_b32_e32 v21, v20
	v_mov_b32_e32 v22, v20
	v_mov_b32_e32 v23, v20
	v_mov_b32_e32 v28, v20
	v_mov_b32_e32 v29, v20
	v_mov_b32_e32 v30, v20
	v_mov_b32_e32 v31, v20
	v_mov_b32_e32 v36, v20
	v_mov_b32_e32 v37, v20
	v_mov_b32_e32 v38, v20
	v_mov_b32_e32 v39, v20
	v_mov_b32_e32 v44, v20
	v_mov_b32_e32 v45, v20
	v_mov_b32_e32 v46, v20
	v_mov_b32_e32 v47, v20
	v_mov_b32_e32 v52, v20
	v_mov_b32_e32 v53, v20
	v_mov_b32_e32 v54, v20
	v_mov_b32_e32 v55, v20
	v_mov_b32_e32 v60, v20
	v_mov_b32_e32 v61, v20
	v_mov_b32_e32 v62, v20
	v_mov_b32_e32 v63, v20
	v_mov_b32_e32 v68, v20
	v_mov_b32_e32 v69, v20
	v_mov_b32_e32 v70, v20
	v_mov_b32_e32 v71, v20
	v_mov_b32_e32 v76, v20
	v_mov_b32_e32 v77, v20
	v_mov_b32_e32 v78, v20
	v_mov_b32_e32 v79, v20
	v_mov_b32_e32 v24, v20
	v_mov_b32_e32 v25, v20
	v_mov_b32_e32 v26, v20
	v_mov_b32_e32 v27, v20
	v_mov_b32_e32 v32, v20
	v_mov_b32_e32 v33, v20
	v_mov_b32_e32 v34, v20
	v_mov_b32_e32 v35, v20
	v_mov_b32_e32 v40, v20
	v_mov_b32_e32 v41, v20
	v_mov_b32_e32 v42, v20
	v_mov_b32_e32 v43, v20
	v_mov_b32_e32 v48, v20
	v_mov_b32_e32 v49, v20
	v_mov_b32_e32 v50, v20
	v_mov_b32_e32 v51, v20
	v_mov_b32_e32 v56, v20
	v_mov_b32_e32 v57, v20
	v_mov_b32_e32 v58, v20
	v_mov_b32_e32 v59, v20
	v_mov_b32_e32 v64, v20
	v_mov_b32_e32 v65, v20
	v_mov_b32_e32 v66, v20
	v_mov_b32_e32 v67, v20
	v_mov_b32_e32 v72, v20
	v_mov_b32_e32 v73, v20
	v_mov_b32_e32 v74, v20
	v_mov_b32_e32 v75, v20
	v_mov_b32_e32 v80, v20
	v_mov_b32_e32 v81, v20
	v_mov_b32_e32 v82, v20
	v_mov_b32_e32 v83, v20
	v_mov_b32_e32 v84, v20
	v_mov_b32_e32 v85, v20
	v_mov_b32_e32 v86, v20
	v_mov_b32_e32 v87, v20
	v_mov_b32_e32 v92, v20
	v_mov_b32_e32 v93, v20
	v_mov_b32_e32 v94, v20
	v_mov_b32_e32 v95, v20
	v_mov_b32_e32 v100, v20
	v_mov_b32_e32 v101, v20
	v_mov_b32_e32 v102, v20
	v_mov_b32_e32 v103, v20
	v_mov_b32_e32 v108, v20
	v_mov_b32_e32 v109, v20
	v_mov_b32_e32 v110, v20
	v_mov_b32_e32 v111, v20
	v_mov_b32_e32 v116, v20
	v_mov_b32_e32 v117, v20
	v_mov_b32_e32 v118, v20
	v_mov_b32_e32 v119, v20
	v_mov_b32_e32 v124, v20
	v_mov_b32_e32 v125, v20
	v_mov_b32_e32 v126, v20
	v_mov_b32_e32 v127, v20
	v_mov_b32_e32 v132, v20
	v_mov_b32_e32 v133, v20
	v_mov_b32_e32 v134, v20
	v_mov_b32_e32 v135, v20
	v_mov_b32_e32 v140, v20
	v_mov_b32_e32 v141, v20
	v_mov_b32_e32 v142, v20
	v_mov_b32_e32 v143, v20
	v_mov_b32_e32 v88, v20
	v_mov_b32_e32 v89, v20
	v_mov_b32_e32 v90, v20
	v_mov_b32_e32 v91, v20
	v_mov_b32_e32 v96, v20
	v_mov_b32_e32 v97, v20
	v_mov_b32_e32 v98, v20
	v_mov_b32_e32 v99, v20
	v_mov_b32_e32 v104, v20
	v_mov_b32_e32 v105, v20
	v_mov_b32_e32 v106, v20
	v_mov_b32_e32 v107, v20
	v_mov_b32_e32 v112, v20
	v_mov_b32_e32 v113, v20
	v_mov_b32_e32 v114, v20
	v_mov_b32_e32 v115, v20
	v_mov_b32_e32 v120, v20
	v_mov_b32_e32 v121, v20
	v_mov_b32_e32 v122, v20
	v_mov_b32_e32 v123, v20
	v_mov_b32_e32 v128, v20
	v_mov_b32_e32 v129, v20
	v_mov_b32_e32 v130, v20
	v_mov_b32_e32 v131, v20
	v_mov_b32_e32 v136, v20
	v_mov_b32_e32 v137, v20
	v_mov_b32_e32 v138, v20
	v_mov_b32_e32 v139, v20
	v_mov_b32_e32 v144, v20
	v_mov_b32_e32 v145, v20
	v_mov_b32_e32 v146, v20
	v_mov_b32_e32 v147, v20
.LBB0_256:
	s_add_u32 s22, s2, 0xfff80800
	s_addc_u32 s23, s3, -1
	s_add_i32 s48, 0, 0x10000
	s_cmp_eq_u32 s35, 28
	s_cselect_b32 s27, s8, s23
	s_cselect_b32 s26, s9, s22
	s_cselect_b32 s23, s15, s34
	s_cselect_b32 s22, s17, s33
	s_add_i32 s50, 0, 0x14000
	v_add_u32_e32 v176, s48, v191
	v_add_u32_e32 v188, s50, v191
	ds_read_b128 v[148:151], v176
	ds_read_b128 v[152:155], v176 offset:1024
	ds_read_b128 v[172:175], v176 offset:2048
	ds_read_b128 v[176:179], v176 offset:3072
	ds_read_b128 v[180:183], v188
	ds_read_b128 v[184:187], v188 offset:1024
	ds_read_b128 v[196:199], v188 offset:2048
	ds_read_b128 v[200:203], v188 offset:3072
	s_add_i32 m0, s39, 0xc000
	ds_read_b128 v[204:207], v194
	ds_read_b128 v[212:215], v194 offset:1024
	ds_read_b128 v[216:219], v194 offset:2048
	ds_read_b128 v[220:223], v194 offset:3072
	ds_read_b128 v[224:227], v194 offset:4096
	ds_read_b128 v[228:231], v194 offset:5120
	ds_read_b128 v[232:235], v194 offset:6144
	ds_read_b128 v[236:239], v194 offset:7168
	global_load_lds_dwordx4 v168, s[2:3]
	s_add_i32 m0, s39, 0xe000
	s_nop 0
	global_load_lds_dwordx4 v170, s[2:3]
	s_waitcnt vmcnt(8)
	s_waitcnt lgkmcnt(0)
	s_barrier
	s_setprio 1
	s_waitcnt lgkmcnt(0)
	v_mfma_f32_16x16x32_bf16 v[144:147], v[148:151], v[204:207], v[144:147]
	v_mfma_f32_16x16x32_bf16 v[136:139], v[172:175], v[204:207], v[136:139]
	v_mfma_f32_16x16x32_bf16 v[128:131], v[148:151], v[216:219], v[128:131]
	v_mfma_f32_16x16x32_bf16 v[120:123], v[172:175], v[216:219], v[120:123]
	v_mfma_f32_16x16x32_bf16 v[112:115], v[148:151], v[224:227], v[112:115]
	v_mfma_f32_16x16x32_bf16 v[104:107], v[172:175], v[224:227], v[104:107]
	v_mfma_f32_16x16x32_bf16 v[96:99], v[148:151], v[232:235], v[96:99]
	v_mfma_f32_16x16x32_bf16 v[88:91], v[172:175], v[232:235], v[88:91]
	v_mfma_f32_16x16x32_bf16 v[144:147], v[152:155], v[212:215], v[144:147]
	v_mfma_f32_16x16x32_bf16 v[136:139], v[176:179], v[212:215], v[136:139]
	v_mfma_f32_16x16x32_bf16 v[128:131], v[152:155], v[220:223], v[128:131]
	v_mfma_f32_16x16x32_bf16 v[120:123], v[176:179], v[220:223], v[120:123]
	v_mfma_f32_16x16x32_bf16 v[112:115], v[152:155], v[228:231], v[112:115]
	v_mfma_f32_16x16x32_bf16 v[104:107], v[176:179], v[228:231], v[104:107]
	v_mfma_f32_16x16x32_bf16 v[96:99], v[152:155], v[236:239], v[96:99]
	v_mfma_f32_16x16x32_bf16 v[88:91], v[176:179], v[236:239], v[88:91]
	s_setprio 0
	s_setprio 1
	v_mfma_f32_16x16x32_bf16 v[140:143], v[180:183], v[204:207], v[140:143]
	v_mfma_f32_16x16x32_bf16 v[132:135], v[196:199], v[204:207], v[132:135]
	v_mfma_f32_16x16x32_bf16 v[124:127], v[180:183], v[216:219], v[124:127]
	v_mfma_f32_16x16x32_bf16 v[116:119], v[196:199], v[216:219], v[116:119]
	v_mfma_f32_16x16x32_bf16 v[108:111], v[180:183], v[224:227], v[108:111]
	v_mfma_f32_16x16x32_bf16 v[100:103], v[196:199], v[224:227], v[100:103]
	v_mfma_f32_16x16x32_bf16 v[92:95], v[180:183], v[232:235], v[92:95]
	v_mfma_f32_16x16x32_bf16 v[84:87], v[196:199], v[232:235], v[84:87]
	v_mfma_f32_16x16x32_bf16 v[140:143], v[184:187], v[212:215], v[140:143]
	v_mfma_f32_16x16x32_bf16 v[132:135], v[200:203], v[212:215], v[132:135]
	v_mfma_f32_16x16x32_bf16 v[124:127], v[184:187], v[220:223], v[124:127]
	v_mfma_f32_16x16x32_bf16 v[116:119], v[200:203], v[220:223], v[116:119]
	v_mfma_f32_16x16x32_bf16 v[108:111], v[184:187], v[228:231], v[108:111]
	v_mfma_f32_16x16x32_bf16 v[100:103], v[200:203], v[228:231], v[100:103]
	v_mfma_f32_16x16x32_bf16 v[92:95], v[184:187], v[236:239], v[92:95]
	v_mfma_f32_16x16x32_bf16 v[84:87], v[200:203], v[236:239], v[84:87]
	s_setprio 0
	s_barrier
	s_add_i32 s48, s48, s28
	s_add_u32 s98, s22, 0x80
	s_addc_u32 s99, s23, 0
	s_add_u32 s100, s26, 0x800
	s_addc_u32 s101, s27, 0
	s_mov_b32 m0, s48
	ds_read_b128 v[204:207], v194 offset:16384
	ds_read_b128 v[212:215], v194 offset:17408
	ds_read_b128 v[216:219], v194 offset:18432
	ds_read_b128 v[220:223], v194 offset:19456
	ds_read_b128 v[224:227], v194 offset:20480
	ds_read_b128 v[228:231], v194 offset:21504
	ds_read_b128 v[232:235], v194 offset:22528
	ds_read_b128 v[236:239], v194 offset:23552
	global_load_lds_dwordx4 v2, s[22:23]
	s_add_i32 m0, s48, 0x2000
	s_add_u32 s48, s22, 0x80000
	s_addc_u32 s49, s23, 0
	s_add_i32 s50, s50, s28
	global_load_lds_dwordx4 v156, s[22:23]
	s_mov_b32 m0, s50
	s_nop 0
	global_load_lds_dwordx4 v2, s[48:49]
	s_add_i32 m0, s50, 0x2000
	s_nop 0
	global_load_lds_dwordx4 v156, s[48:49]
	s_mov_b32 m0, s39
	s_nop 0
	global_load_lds_dwordx4 v160, s[26:27]
	s_mov_b32 m0, s41
	s_nop 0
	global_load_lds_dwordx4 v158, s[26:27]
	s_waitcnt vmcnt(8)
	s_waitcnt lgkmcnt(0)
	s_barrier
	s_setprio 1
	s_waitcnt lgkmcnt(0)
	v_mfma_f32_16x16x32_bf16 v[80:83], v[148:151], v[204:207], v[80:83]
	v_mfma_f32_16x16x32_bf16 v[72:75], v[172:175], v[204:207], v[72:75]
	v_mfma_f32_16x16x32_bf16 v[64:67], v[148:151], v[216:219], v[64:67]
	v_mfma_f32_16x16x32_bf16 v[56:59], v[172:175], v[216:219], v[56:59]
	v_mfma_f32_16x16x32_bf16 v[48:51], v[148:151], v[224:227], v[48:51]
	v_mfma_f32_16x16x32_bf16 v[40:43], v[172:175], v[224:227], v[40:43]
	v_mfma_f32_16x16x32_bf16 v[32:35], v[148:151], v[232:235], v[32:35]
	v_mfma_f32_16x16x32_bf16 v[24:27], v[172:175], v[232:235], v[24:27]
	v_mfma_f32_16x16x32_bf16 v[80:83], v[152:155], v[212:215], v[80:83]
	v_mfma_f32_16x16x32_bf16 v[72:75], v[176:179], v[212:215], v[72:75]
	v_mfma_f32_16x16x32_bf16 v[64:67], v[152:155], v[220:223], v[64:67]
	v_mfma_f32_16x16x32_bf16 v[56:59], v[176:179], v[220:223], v[56:59]
	v_mfma_f32_16x16x32_bf16 v[48:51], v[152:155], v[228:231], v[48:51]
	v_mfma_f32_16x16x32_bf16 v[40:43], v[176:179], v[228:231], v[40:43]
	v_mfma_f32_16x16x32_bf16 v[32:35], v[152:155], v[236:239], v[32:35]
	v_mfma_f32_16x16x32_bf16 v[24:27], v[176:179], v[236:239], v[24:27]
	s_setprio 0
	s_setprio 1
	v_mfma_f32_16x16x32_bf16 v[76:79], v[180:183], v[204:207], v[76:79]
	v_mfma_f32_16x16x32_bf16 v[68:71], v[196:199], v[204:207], v[68:71]
	v_mfma_f32_16x16x32_bf16 v[60:63], v[180:183], v[216:219], v[60:63]
	v_mfma_f32_16x16x32_bf16 v[52:55], v[196:199], v[216:219], v[52:55]
	v_mfma_f32_16x16x32_bf16 v[44:47], v[180:183], v[224:227], v[44:47]
	v_mfma_f32_16x16x32_bf16 v[36:39], v[196:199], v[224:227], v[36:39]
	v_mfma_f32_16x16x32_bf16 v[28:31], v[180:183], v[232:235], v[28:31]
	v_mfma_f32_16x16x32_bf16 v[20:23], v[196:199], v[232:235], v[20:23]
	v_mfma_f32_16x16x32_bf16 v[76:79], v[184:187], v[212:215], v[76:79]
	v_mfma_f32_16x16x32_bf16 v[68:71], v[200:203], v[212:215], v[68:71]
	v_mfma_f32_16x16x32_bf16 v[60:63], v[184:187], v[220:223], v[60:63]
	v_mfma_f32_16x16x32_bf16 v[52:55], v[200:203], v[220:223], v[52:55]
	v_mfma_f32_16x16x32_bf16 v[44:47], v[184:187], v[228:231], v[44:47]
	v_mfma_f32_16x16x32_bf16 v[36:39], v[200:203], v[228:231], v[36:39]
	v_mfma_f32_16x16x32_bf16 v[28:31], v[184:187], v[236:239], v[28:31]
	v_mfma_f32_16x16x32_bf16 v[20:23], v[200:203], v[236:239], v[20:23]
	s_setprio 0
	s_barrier
	s_add_i32 s48, 0, 0x18000
	s_add_i32 s49, 0, 0x1c000
	v_add_u32_e32 v176, s48, v191
	v_add_u32_e32 v195, s49, v191
	ds_read_b128 v[148:151], v176
	ds_read_b128 v[152:155], v176 offset:1024
	ds_read_b128 v[172:175], v176 offset:2048
	ds_read_b128 v[176:179], v176 offset:3072
	ds_read_b128 v[180:183], v195
	ds_read_b128 v[184:187], v195 offset:1024
	ds_read_b128 v[196:199], v195 offset:2048
	ds_read_b128 v[200:203], v195 offset:3072
	s_add_u32 s26, s26, 0x80000
	s_addc_u32 s27, s27, 0
	s_mov_b32 m0, s42
	ds_read_b128 v[204:207], v194 offset:32768
	ds_read_b128 v[212:215], v194 offset:33792
	ds_read_b128 v[216:219], v194 offset:34816
	ds_read_b128 v[220:223], v194 offset:35840
	ds_read_b128 v[224:227], v194 offset:36864
	ds_read_b128 v[228:231], v194 offset:37888
	ds_read_b128 v[232:235], v194 offset:38912
	ds_read_b128 v[236:239], v194 offset:39936
	global_load_lds_dwordx4 v160, s[26:27]
	s_mov_b32 m0, s43
	s_nop 0
	global_load_lds_dwordx4 v158, s[26:27]
	s_waitcnt vmcnt(8)
	s_waitcnt lgkmcnt(0)
	s_barrier
	s_setprio 1
	s_waitcnt lgkmcnt(0)
	v_mfma_f32_16x16x32_bf16 v[144:147], v[148:151], v[204:207], v[144:147]
	v_mfma_f32_16x16x32_bf16 v[136:139], v[172:175], v[204:207], v[136:139]
	v_mfma_f32_16x16x32_bf16 v[128:131], v[148:151], v[216:219], v[128:131]
	v_mfma_f32_16x16x32_bf16 v[120:123], v[172:175], v[216:219], v[120:123]
	v_mfma_f32_16x16x32_bf16 v[112:115], v[148:151], v[224:227], v[112:115]
	v_mfma_f32_16x16x32_bf16 v[104:107], v[172:175], v[224:227], v[104:107]
	v_mfma_f32_16x16x32_bf16 v[96:99], v[148:151], v[232:235], v[96:99]
	v_mfma_f32_16x16x32_bf16 v[88:91], v[172:175], v[232:235], v[88:91]
	v_mfma_f32_16x16x32_bf16 v[144:147], v[152:155], v[212:215], v[144:147]
	v_mfma_f32_16x16x32_bf16 v[136:139], v[176:179], v[212:215], v[136:139]
	v_mfma_f32_16x16x32_bf16 v[128:131], v[152:155], v[220:223], v[128:131]
	v_mfma_f32_16x16x32_bf16 v[120:123], v[176:179], v[220:223], v[120:123]
	v_mfma_f32_16x16x32_bf16 v[112:115], v[152:155], v[228:231], v[112:115]
	v_mfma_f32_16x16x32_bf16 v[104:107], v[176:179], v[228:231], v[104:107]
	v_mfma_f32_16x16x32_bf16 v[96:99], v[152:155], v[236:239], v[96:99]
	v_mfma_f32_16x16x32_bf16 v[88:91], v[176:179], v[236:239], v[88:91]
	s_setprio 0
	s_setprio 1
	v_mfma_f32_16x16x32_bf16 v[140:143], v[180:183], v[204:207], v[140:143]
	v_mfma_f32_16x16x32_bf16 v[132:135], v[196:199], v[204:207], v[132:135]
	v_mfma_f32_16x16x32_bf16 v[124:127], v[180:183], v[216:219], v[124:127]
	v_mfma_f32_16x16x32_bf16 v[116:119], v[196:199], v[216:219], v[116:119]
	v_mfma_f32_16x16x32_bf16 v[108:111], v[180:183], v[224:227], v[108:111]
	v_mfma_f32_16x16x32_bf16 v[100:103], v[196:199], v[224:227], v[100:103]
	v_mfma_f32_16x16x32_bf16 v[92:95], v[180:183], v[232:235], v[92:95]
	v_mfma_f32_16x16x32_bf16 v[84:87], v[196:199], v[232:235], v[84:87]
	v_mfma_f32_16x16x32_bf16 v[140:143], v[184:187], v[212:215], v[140:143]
	v_mfma_f32_16x16x32_bf16 v[132:135], v[200:203], v[212:215], v[132:135]
	v_mfma_f32_16x16x32_bf16 v[124:127], v[184:187], v[220:223], v[124:127]
	v_mfma_f32_16x16x32_bf16 v[116:119], v[200:203], v[220:223], v[116:119]
	v_mfma_f32_16x16x32_bf16 v[108:111], v[184:187], v[228:231], v[108:111]
	v_mfma_f32_16x16x32_bf16 v[100:103], v[200:203], v[228:231], v[100:103]
	v_mfma_f32_16x16x32_bf16 v[92:95], v[184:187], v[236:239], v[92:95]
	v_mfma_f32_16x16x32_bf16 v[84:87], v[200:203], v[236:239], v[84:87]
	s_setprio 0
	s_barrier
	s_add_i32 s26, s48, s28
	s_mov_b32 m0, s26
	ds_read_b128 v[204:207], v194 offset:49152
	ds_read_b128 v[212:215], v194 offset:50176
	ds_read_b128 v[216:219], v194 offset:51200
	ds_read_b128 v[220:223], v194 offset:52224
	ds_read_b128 v[224:227], v194 offset:53248
	ds_read_b128 v[228:231], v194 offset:54272
	ds_read_b128 v[232:235], v194 offset:55296
	ds_read_b128 v[236:239], v194 offset:56320
	global_load_lds_dwordx4 v2, s[98:99]
	s_add_i32 m0, s26, 0x2000
	s_add_u32 s22, s22, 0x80080
	s_addc_u32 s23, s23, 0
	s_add_i32 s26, s49, s28
	global_load_lds_dwordx4 v156, s[98:99]
	s_mov_b32 m0, s26
	s_nop 0
	global_load_lds_dwordx4 v2, s[22:23]
	s_add_i32 m0, s26, 0x2000
	s_nop 0
	global_load_lds_dwordx4 v156, s[22:23]
	s_mov_b32 m0, s44
	s_nop 0
	global_load_lds_dwordx4 v160, s[100:101]
	s_mov_b32 m0, s45
	s_nop 0
	global_load_lds_dwordx4 v158, s[100:101]
	s_waitcnt vmcnt(8)
	s_waitcnt lgkmcnt(0)
	s_barrier
	s_setprio 1
	s_waitcnt lgkmcnt(0)
	v_mfma_f32_16x16x32_bf16 v[80:83], v[148:151], v[204:207], v[80:83]
	v_mfma_f32_16x16x32_bf16 v[72:75], v[172:175], v[204:207], v[72:75]
	v_mfma_f32_16x16x32_bf16 v[64:67], v[148:151], v[216:219], v[64:67]
	v_mfma_f32_16x16x32_bf16 v[56:59], v[172:175], v[216:219], v[56:59]
	v_mfma_f32_16x16x32_bf16 v[48:51], v[148:151], v[224:227], v[48:51]
	v_mfma_f32_16x16x32_bf16 v[40:43], v[172:175], v[224:227], v[40:43]
	v_mfma_f32_16x16x32_bf16 v[32:35], v[148:151], v[232:235], v[32:35]
	v_mfma_f32_16x16x32_bf16 v[24:27], v[172:175], v[232:235], v[24:27]
	v_mfma_f32_16x16x32_bf16 v[80:83], v[152:155], v[212:215], v[80:83]
	v_mfma_f32_16x16x32_bf16 v[72:75], v[176:179], v[212:215], v[72:75]
	v_mfma_f32_16x16x32_bf16 v[64:67], v[152:155], v[220:223], v[64:67]
	v_mfma_f32_16x16x32_bf16 v[56:59], v[176:179], v[220:223], v[56:59]
	v_mfma_f32_16x16x32_bf16 v[48:51], v[152:155], v[228:231], v[48:51]
	v_mfma_f32_16x16x32_bf16 v[40:43], v[176:179], v[228:231], v[40:43]
	v_mfma_f32_16x16x32_bf16 v[32:35], v[152:155], v[236:239], v[32:35]
	v_mfma_f32_16x16x32_bf16 v[24:27], v[176:179], v[236:239], v[24:27]
	s_setprio 0
	s_setprio 1
	v_mfma_f32_16x16x32_bf16 v[76:79], v[180:183], v[204:207], v[76:79]
	v_mfma_f32_16x16x32_bf16 v[68:71], v[196:199], v[204:207], v[68:71]
	v_mfma_f32_16x16x32_bf16 v[60:63], v[180:183], v[216:219], v[60:63]
	v_mfma_f32_16x16x32_bf16 v[52:55], v[196:199], v[216:219], v[52:55]
	v_mfma_f32_16x16x32_bf16 v[44:47], v[180:183], v[224:227], v[44:47]
	v_mfma_f32_16x16x32_bf16 v[36:39], v[196:199], v[224:227], v[36:39]
	v_mfma_f32_16x16x32_bf16 v[28:31], v[180:183], v[232:235], v[28:31]
	v_mfma_f32_16x16x32_bf16 v[20:23], v[196:199], v[232:235], v[20:23]
	v_mfma_f32_16x16x32_bf16 v[76:79], v[184:187], v[212:215], v[76:79]
	v_mfma_f32_16x16x32_bf16 v[68:71], v[200:203], v[212:215], v[68:71]
	v_mfma_f32_16x16x32_bf16 v[60:63], v[184:187], v[220:223], v[60:63]
	v_mfma_f32_16x16x32_bf16 v[52:55], v[200:203], v[220:223], v[52:55]
	v_mfma_f32_16x16x32_bf16 v[44:47], v[184:187], v[228:231], v[44:47]
	v_mfma_f32_16x16x32_bf16 v[36:39], v[200:203], v[228:231], v[36:39]
	v_mfma_f32_16x16x32_bf16 v[28:31], v[184:187], v[236:239], v[28:31]
	v_mfma_f32_16x16x32_bf16 v[20:23], v[200:203], v[236:239], v[20:23]
	s_setprio 0
	s_barrier
	s_add_i32 s35, s35, 2
	s_add_u32 s2, s2, 0x1000
	s_addc_u32 s3, s3, 0
	s_add_u32 s33, s33, 0x100
	s_addc_u32 s34, s34, 0
	s_cmp_gt_u32 s35, 29
	s_cbranch_scc0 .LBB0_256
	s_and_b64 vcc, exec, s[12:13]
	s_cbranch_vccz .LBB0_259
	s_barrier

.LBB0_476:
	v_readlane_b32 s0, v255, 9
	v_readlane_b32 s1, v255, 10
	s_mov_b32 s3, s1
	s_lshr_b32 s2, s40, 3
	v_readlane_b32 s0, v252, 3
	v_writelane_b32 v255, s2, 9
	s_cmp_ge_i32 s0, s2
	v_readfirstlane_b32 s6, v210
	v_writelane_b32 v255, s3, 10
	s_cbranch_scc1 .LBB0_500
	v_lshlrev_b32_e32 v2, 4, v210
	s_waitcnt vmcnt(0)
	v_add_u32_e32 v21, 0x2000, v2
	v_ashrrev_i32_e32 v20, 31, v21
	v_lshrrev_b32_e32 v20, 22, v20
	v_add_u32_e32 v20, v21, v20
	v_ashrrev_i32_e32 v20, 10, v20
	v_mul_i32_i24_e32 v22, 0x400, v20
	v_sub_u32_e32 v21, v21, v22
	v_lshrrev_b32_e32 v22, 4, v21
	v_bitop3_b32 v22, v22, v21, 32 bitop3:0x6c
	v_ashrrev_i32_e32 v21, 31, v22
	v_lshrrev_b32_e32 v21, 26, v21
	s_ashr_i32 s8, s6, 6
	v_readlane_b32 s0, v255, 11
	v_add_u32_e32 v23, v22, v21
	v_lshlrev_b32_e32 v24, 3, v20
	s_lshl_b32 s7, s8, 10
	s_lshl_b32 s0, s0, 25
	v_readlane_b32 s1, v253, 14
	v_ashrrev_i32_e32 v21, 6, v23
	v_and_b32_e32 v24, -16, v24
	s_add_u32 s28, s1, s0
	v_readlane_b32 s0, v253, 15
	v_add_u32_e32 v24, v21, v24
	s_addc_u32 s29, s0, 0
	v_and_b32_e32 v25, 3, v21
	s_mov_b32 s0, 0xfffe0
	v_lshrrev_b32_e32 v26, 2, v24
	v_lshlrev_b32_e32 v27, 1, v24
	v_and_b32_e32 v23, 0xc0, v23
	v_and_or_b32 v25, v24, s0, v25
	v_and_b32_e32 v26, 4, v26
	v_and_b32_e32 v27, 24, v27
	v_sub_u32_e32 v22, v22, v23
	v_mov_b32_e32 v30, 1
	v_or3_b32 v25, v25, v26, v27
	v_lshlrev_b32_e32 v26, 5, v20
	v_ashrrev_i16_sdwa v22, v30, sext(v22) dst_sel:DWORD dst_unused:UNUSED_PAD src0_sel:DWORD src1_sel:BYTE_0
	v_and_b32_e32 v26, 32, v26
	v_bfe_i32 v22, v22, 0, 16
	v_add_lshl_u32 v23, v26, v22, 1
	v_lshl_add_u32 v148, v25, 12, v23
	v_lshl_add_u32 v150, v24, 12, v23
	v_bfe_i32 v23, v210, 27, 1
	v_lshrrev_b32_e32 v23, 22, v23
	v_add_u32_e32 v23, v2, v23
	v_and_b32_e32 v23, 0xfffffc00, v23
	v_sub_u32_e32 v2, v2, v23
	v_lshrrev_b32_e32 v23, 4, v2
	v_ashrrev_i32_e32 v24, 31, v210
	v_bitop3_b32 v2, v23, v2, 32 bitop3:0x6c
	v_lshrrev_b32_e32 v24, 26, v24
	v_ashrrev_i32_e32 v23, 31, v2
	v_add_u32_e32 v24, v210, v24
	v_lshrrev_b32_e32 v23, 26, v23
	v_ashrrev_i32_e32 v24, 6, v24
	v_add_u32_e32 v25, v2, v23
	v_lshlrev_b32_e32 v26, 3, v24
	v_ashrrev_i32_e32 v23, 6, v25
	v_and_b32_e32 v26, -16, v26
	v_add_u32_e32 v26, v23, v26
	v_and_b32_e32 v27, 3, v23
	s_lshr_b32 s41, s40, 5
	s_lshr_b32 s40, s40, 6
	v_and_or_b32 v27, v26, s0, v27
	v_readlane_b32 s0, v254, 32
	s_or_b32 s42, s40, 1
	v_readlane_b32 s1, v254, 33
	v_lshrrev_b32_e32 v28, 2, v26
	v_lshlrev_b32_e32 v29, 1, v26
	s_and_b64 s[0:1], s[0:1], exec
	v_and_b32_e32 v28, 4, v28
	v_and_b32_e32 v29, 24, v29
	s_cselect_b32 s0, s42, s40
	s_abs_i32 s43, s41
	v_or3_b32 v27, v27, v28, v29
	v_cvt_f32_u32_e32 v29, s43
	v_and_b32_e32 v25, 0xc0, v25
	v_sub_u32_e32 v2, v2, v25
	v_ashrrev_i16_sdwa v2, v30, sext(v2) dst_sel:DWORD dst_unused:UNUSED_PAD src0_sel:DWORD src1_sel:BYTE_0
	v_bfe_i32 v25, v2, 0, 16
	v_rcp_iflag_f32_e32 v2, v29
	v_readlane_b32 s1, v252, 43
	s_sub_i32 s3, 0, s43
	s_mul_i32 s0, s0, s1
	v_mul_f32_e32 v2, 0x4f7ffffe, v2
	v_cvt_u32_f32_e32 v2, v2
	v_readlane_b32 s1, v252, 44
	s_add_i32 s0, s0, s1
	s_abs_i32 s2, s0
	v_readfirstlane_b32 s45, v2
	s_mul_i32 s3, s3, s45
	s_mul_hi_u32 s3, s45, s3
	s_add_i32 s45, s45, s3
	s_mul_hi_u32 s3, s2, s45
	s_mul_i32 s9, s3, s43
	s_ashr_i32 s1, s0, 31
	s_ashr_i32 s44, s41, 31
	s_sub_i32 s2, s2, s9
	s_xor_b32 s1, s1, s44
	s_add_i32 s9, s3, 1
	s_sub_i32 s12, s2, s43
	s_cmp_ge_u32 s2, s43
	s_cselect_b32 s3, s9, s3
	s_cselect_b32 s2, s12, s2
	s_add_i32 s9, s3, 1
	s_cmp_ge_u32 s2, s43
	s_cselect_b32 s2, s9, s3
	s_xor_b32 s2, s2, s1
	s_sub_i32 s1, s2, s1
	s_lshl_b32 s2, s1, 3
	s_sub_i32 s3, 32, s2
	s_min_i32 s3, s3, 8
	s_abs_i32 s9, s3
	v_cvt_f32_u32_e32 v29, s9
	v_lshlrev_b32_e32 v28, 5, v24
	v_and_b32_e32 v28, 32, v28
	v_add_lshl_u32 v28, v28, v25, 1
	v_lshl_add_u32 v152, v26, 12, v28
	v_lshrrev_b32_e32 v152, 7, v210
	v_lshlrev_b32_e32 v152, 16, v152
	v_bfe_u32 v248, v210, 6, 1
	v_lshl_or_b32 v152, v248, 10, v152
	v_and_b32_e32 v248, 63, v210
	v_lshl_or_b32 v152, v248, 4, v152
	v_add_u32_e32 v150, 0x40000, v152
	s_movk_i32 s100, 0x800
	s_mov_b32 s101, 0
	v_rcp_iflag_f32_e32 v26, v29
	s_sub_i32 s13, 0, s9
	s_mul_i32 s1, s1, s41
	s_sub_i32 s0, s0, s1
	v_mul_f32_e32 v26, 0x4f7ffffe, v26
	v_cvt_u32_f32_e32 v26, v26
	s_abs_i32 s12, s0
	s_xor_b32 s1, s0, s3
	s_ashr_i32 s1, s1, 31
	v_readfirstlane_b32 s14, v26
	s_mul_i32 s13, s13, s14
	s_mul_hi_u32 s13, s14, s13
	s_add_i32 s14, s14, s13
	s_mul_hi_u32 s13, s12, s14
	s_mul_i32 s14, s13, s9
	s_sub_i32 s12, s12, s14
	s_add_i32 s14, s13, 1
	s_sub_i32 s15, s12, s9
	s_cmp_ge_u32 s12, s9
	s_cselect_b32 s13, s14, s13
	s_cselect_b32 s12, s15, s12
	s_add_i32 s14, s13, 1
	s_cmp_ge_u32 s12, s9
	s_cselect_b32 s9, s14, s13
	s_xor_b32 s9, s9, s1
	s_sub_i32 s12, s9, s1
	s_mul_i32 s1, s12, s3
	s_sub_i32 s0, s0, s1
	s_add_i32 s2, s0, s2
	s_ashr_i32 s3, s2, 31
	s_ashr_i32 s13, s12, 31
	s_lshl_b64 s[0:1], s[2:3], 20
	s_lshl_b64 s[14:15], s[12:13], 20
	s_add_u32 s26, s28, s14
	s_addc_u32 s27, s29, s15
	s_add_i32 s13, s7, 0
	v_lshl_add_u32 v2, v27, 12, v28
	s_add_i32 m0, s13, 0x10000
	s_nop 0
	global_load_lds_dwordx4 v2, s[26:27]
	s_add_i32 m0, s13, 0x12000
	s_add_u32 s14, s26, 0x80000
	global_load_lds_dwordx4 v148, s[26:27]
	s_addc_u32 s15, s27, 0
	s_add_i32 m0, s13, 0x14000
	s_nop 0
	global_load_lds_dwordx4 v2, s[14:15]
	s_add_i32 m0, s13, 0x16000
	s_nop 0
	global_load_lds_dwordx4 v148, s[14:15]
	v_readlane_b32 s14, v254, 39
	v_readlane_b32 s15, v254, 40
	s_add_u32 s22, s14, s0
	s_addc_u32 s23, s15, s1
	s_add_i32 s46, s13, 0x2000
	s_mov_b32 m0, s13
	s_add_u32 s0, s22, 0x80000
	global_load_lds_dwordx4 v152, s[22:23]
	s_mov_b32 m0, s46
	s_addc_u32 s1, s23, 0
	s_add_i32 s47, s13, 0x4000
	global_load_lds_dwordx4 v150, s[22:23]
	s_mov_b32 m0, s47
	s_add_i32 s48, s13, 0x6000
	global_load_lds_dwordx4 v152, s[0:1]
	s_mov_b32 m0, s48
	s_andn2_b64 vcc, exec, s[4:5]
	global_load_lds_dwordx4 v150, s[0:1]
	s_cbranch_vccnz .LBB0_481
	v_add_f32_e32 v16, v16, v17
	v_add_f32_e32 v17, v18, v19
	v_add_f32_e32 v16, v16, v17
	v_add_f32_e32 v12, v12, v13
	v_add_f32_e32 v13, v14, v15
	v_add_f32_e32 v4, v4, v5
	v_add_f32_e32 v5, v6, v7
	v_and_b32_e32 v6, 64, v208
	v_add_f32_e32 v16, 0, v16
	v_add_f32_e32 v12, v12, v13
	v_add_f32_e32 v8, v8, v9
	v_add_f32_e32 v9, v10, v11
	v_add_f32_e32 v4, v4, v5
	v_xor_b32_e32 v5, 1, v208
	v_add_u32_e32 v6, 64, v6
	v_add_f32_e32 v12, v16, v12
	v_add_f32_e32 v8, v8, v9
	v_cmp_lt_i32_e32 vcc, v5, v6
	v_add_f32_e32 v8, v12, v8
	v_add_f32_e32 v4, v8, v4
	v_cndmask_b32_e32 v5, v208, v5, vcc
	v_lshlrev_b32_e32 v5, 2, v5
	ds_bpermute_b32 v5, v5, v4
	v_and_b32_e32 v6, 1, v210
	v_cmp_eq_u32_e32 vcc, 0, v6
	s_and_saveexec_b64 s[0:1], vcc
	s_cbranch_execz .LBB0_480
	s_waitcnt lgkmcnt(0)
	v_add_f32_e32 v4, v4, v5
	v_fmamk_f32 v4, v4, 0x3a000000, v1
	v_rsq_f32_e32 v4, v4
	v_lshl_add_u32 v5, v210, 1, 0
	v_add_u32_e32 v5, 0x21000, v5
	ds_write_b32 v5, v4

.LBB0_483:
	v_bfe_u32 v13, v210, 4, 2
	v_and_b32_e32 v12, 15, v210
	v_lshlrev_b32_e32 v163, 4, v13
	v_lshl_or_b32 v162, s3, 6, v12
	v_lshl_or_b32 v14, v12, 6, v163
	v_lshlrev_b32_e32 v12, 2, v12
	s_and_b32 s8, s8, 3
	s_lshl_b32 s4, s3, 13
	v_and_b32_e32 v15, 32, v12
	s_add_i32 m0, s13, 0x18000
	v_lshl_add_u64 v[6:7], v[6:7], 0, s[30:31]
	v_bitop3_b32 v16, v14, s4, v15 bitop3:0xde
	s_lshl_b32 s4, s8, 12
	s_waitcnt vmcnt(2)
	s_barrier
	global_load_lds_dwordx4 v[6:7], off
	v_lshl_add_u64 v[6:7], v[8:9], 0, s[30:31]
	s_add_i32 m0, s13, 0x1a000
	s_add_i32 s49, s13, 0x8000
	s_add_i32 s50, s13, 0xa000
	v_bitop3_b32 v168, s4, v14, v15 bitop3:0xf6
	global_load_lds_dwordx4 v[6:7], off
	v_lshl_add_u64 v[4:5], v[4:5], 0, s[100:101]
	s_mov_b32 m0, s49
	s_add_u32 s4, s26, 0x80080
	global_load_lds_dwordx4 v[4:5], off
	v_lshl_add_u64 v[4:5], v[10:11], 0, s[100:101]
	s_mov_b32 m0, s50
	s_addc_u32 s5, s27, 0
	global_load_lds_dwordx4 v[4:5], off
	s_add_i32 m0, s13, 0x1c000
	v_lshl_add_u64 v[4:5], s[4:5], 0, v[2:3]
	global_load_lds_dwordx4 v[4:5], off
	v_lshl_add_u64 v[4:5], s[4:5], 0, v[148:149]
	s_add_i32 m0, s13, 0x1e000
	s_cmpk_lt_u32 s6, 0x100
	global_load_lds_dwordx4 v[4:5], off
	s_cselect_b64 s[4:5], -1, 0
	s_lshl_b32 s51, s8, 6
	v_readlane_b32 s8, v252, 45
	v_lshlrev_b32_e32 v4, 5, v13
	v_mov_b32_e32 v5, v3
	v_readlane_b32 s9, v252, 46
	s_lshl_b32 s3, s3, 8
	s_waitcnt vmcnt(6)
	s_add_i32 s3, s3, 0
	v_lshl_add_u64 v[154:155], s[8:9], 0, v[4:5]
	v_lshlrev_b32_e32 v4, 15, v24
	v_and_b32_e32 v4, 0xffff0000, v4
	v_lshl_add_u32 v4, v23, 12, v4
	v_and_b32_e32 v5, 1, v24
	v_lshl_or_b32 v4, v5, 6, v4
	v_lshl_add_u32 v156, v25, 1, v4
	v_lshlrev_b32_e32 v4, 15, v20
	v_and_b32_e32 v4, 0xffff0000, v4
	v_lshl_add_u32 v4, v21, 12, v4
	v_and_b32_e32 v5, 1, v20
	s_add_i32 s3, s3, 0x21000
	v_lshl_or_b32 v4, v5, 6, v4
	v_add_u32_e32 v169, s3, v12
	v_mov_b32_e32 v157, v3
	v_lshl_add_u32 v158, v22, 1, v4
	v_mov_b32_e32 v156, v152
	v_mov_b32_e32 v158, v150
	v_mov_b32_e32 v159, v3
	s_mov_b32 s52, 0
	v_add_u32_e32 v170, 0, v16
	s_barrier
	s_branch .LBB0_486

.LBB0_488:
	s_ashr_i32 s17, s16, 31
	s_lshl_b64 s[8:9], s[16:17], 20
	v_readlane_b32 s18, v254, 39
	v_readlane_b32 s19, v254, 40
	s_add_u32 s18, s18, s8
	s_addc_u32 s19, s19, s9
	s_and_b64 s[8:9], s[36:37], exec
	s_cselect_b32 s3, s19, s23
	s_cselect_b32 s6, s18, s22
	s_ashr_i32 s15, s14, 31
	s_lshl_b64 s[8:9], s[14:15], 20
	s_add_u32 s20, s28, s8
	s_addc_u32 s21, s29, s9
	s_and_b64 s[8:9], s[36:37], exec
	s_cselect_b32 s8, s21, s27
	s_cselect_b32 s9, s20, s26
	s_add_u32 s22, s22, 0x80800
	s_addc_u32 s23, s23, 0
	s_add_u32 s15, s26, 0x100
	v_mov_b32_e32 v12, 0
	s_addc_u32 s17, s27, 0
	s_mov_b32 s33, -2
	v_mov_b32_e32 v13, v12
	v_mov_b32_e32 v14, v12
	v_mov_b32_e32 v15, v12
	v_mov_b32_e32 v16, v12
	v_mov_b32_e32 v17, v12
	v_mov_b32_e32 v18, v12
	v_mov_b32_e32 v19, v12
	v_mov_b32_e32 v20, v12
	v_mov_b32_e32 v21, v12
	v_mov_b32_e32 v22, v12
	v_mov_b32_e32 v23, v12
	v_mov_b32_e32 v28, v12
	v_mov_b32_e32 v29, v12
	v_mov_b32_e32 v30, v12
	v_mov_b32_e32 v31, v12
	v_mov_b32_e32 v36, v12
	v_mov_b32_e32 v37, v12
	v_mov_b32_e32 v38, v12
	v_mov_b32_e32 v39, v12
	v_mov_b32_e32 v44, v12
	v_mov_b32_e32 v45, v12
	v_mov_b32_e32 v46, v12
	v_mov_b32_e32 v47, v12
	v_mov_b32_e32 v52, v12
	v_mov_b32_e32 v53, v12
	v_mov_b32_e32 v54, v12
	v_mov_b32_e32 v55, v12
	v_mov_b32_e32 v60, v12
	v_mov_b32_e32 v61, v12
	v_mov_b32_e32 v62, v12
	v_mov_b32_e32 v63, v12
	v_mov_b32_e32 v24, v12
	v_mov_b32_e32 v25, v12
	v_mov_b32_e32 v26, v12
	v_mov_b32_e32 v27, v12
	v_mov_b32_e32 v32, v12
	v_mov_b32_e32 v33, v12
	v_mov_b32_e32 v34, v12
	v_mov_b32_e32 v35, v12
	v_mov_b32_e32 v40, v12
	v_mov_b32_e32 v41, v12
	v_mov_b32_e32 v42, v12
	v_mov_b32_e32 v43, v12
	v_mov_b32_e32 v48, v12
	v_mov_b32_e32 v49, v12
	v_mov_b32_e32 v50, v12
	v_mov_b32_e32 v51, v12
	v_mov_b32_e32 v56, v12
	v_mov_b32_e32 v57, v12
	v_mov_b32_e32 v58, v12
	v_mov_b32_e32 v59, v12
	v_mov_b32_e32 v64, v12
	v_mov_b32_e32 v65, v12
	v_mov_b32_e32 v66, v12
	v_mov_b32_e32 v67, v12
	v_mov_b32_e32 v68, v12
	v_mov_b32_e32 v69, v12
	v_mov_b32_e32 v70, v12
	v_mov_b32_e32 v71, v12
	v_mov_b32_e32 v72, v12
	v_mov_b32_e32 v73, v12
	v_mov_b32_e32 v74, v12
	v_mov_b32_e32 v75, v12
	v_mov_b32_e32 v76, v12
	v_mov_b32_e32 v77, v12
	v_mov_b32_e32 v78, v12
	v_mov_b32_e32 v79, v12
	v_mov_b32_e32 v80, v12
	v_mov_b32_e32 v81, v12
	v_mov_b32_e32 v82, v12
	v_mov_b32_e32 v83, v12
	v_mov_b32_e32 v84, v12
	v_mov_b32_e32 v85, v12
	v_mov_b32_e32 v86, v12
	v_mov_b32_e32 v87, v12
	v_mov_b32_e32 v92, v12
	v_mov_b32_e32 v93, v12
	v_mov_b32_e32 v94, v12
	v_mov_b32_e32 v95, v12
	v_mov_b32_e32 v100, v12
	v_mov_b32_e32 v101, v12
	v_mov_b32_e32 v102, v12
	v_mov_b32_e32 v103, v12
	v_mov_b32_e32 v108, v12
	v_mov_b32_e32 v109, v12
	v_mov_b32_e32 v110, v12
	v_mov_b32_e32 v111, v12
	v_mov_b32_e32 v116, v12
	v_mov_b32_e32 v117, v12
	v_mov_b32_e32 v118, v12
	v_mov_b32_e32 v119, v12
	v_mov_b32_e32 v124, v12
	v_mov_b32_e32 v125, v12
	v_mov_b32_e32 v126, v12
	v_mov_b32_e32 v127, v12
	v_mov_b32_e32 v88, v12
	v_mov_b32_e32 v89, v12
	v_mov_b32_e32 v90, v12
	v_mov_b32_e32 v91, v12
	v_mov_b32_e32 v96, v12
	v_mov_b32_e32 v97, v12
	v_mov_b32_e32 v98, v12
	v_mov_b32_e32 v99, v12
	v_mov_b32_e32 v104, v12
	v_mov_b32_e32 v105, v12
	v_mov_b32_e32 v106, v12
	v_mov_b32_e32 v107, v12
	v_mov_b32_e32 v112, v12
	v_mov_b32_e32 v113, v12
	v_mov_b32_e32 v114, v12
	v_mov_b32_e32 v115, v12
	v_mov_b32_e32 v120, v12
	v_mov_b32_e32 v121, v12
	v_mov_b32_e32 v122, v12
	v_mov_b32_e32 v123, v12
	v_mov_b32_e32 v128, v12
	v_mov_b32_e32 v129, v12
	v_mov_b32_e32 v130, v12
	v_mov_b32_e32 v131, v12
	v_mov_b32_e32 v132, v12
	v_mov_b32_e32 v133, v12
	v_mov_b32_e32 v134, v12
	v_mov_b32_e32 v135, v12
	v_mov_b32_e32 v136, v12
	v_mov_b32_e32 v137, v12
	v_mov_b32_e32 v138, v12
	v_mov_b32_e32 v139, v12
.LBB0_489:
	s_add_u32 s26, s22, 0xfff80800
	s_addc_u32 s27, s23, -1
	s_add_i32 s34, 0, 0x10000
	s_cmp_eq_u32 s33, 28
	s_cselect_b32 s39, s3, s27
	s_cselect_b32 s38, s6, s26
	s_cselect_b32 s27, s8, s17
	s_cselect_b32 s26, s9, s15
	s_add_i32 s53, 0, 0x14000
	v_add_u32_e32 v144, s34, v168
	v_add_u32_e32 v160, s53, v168
	ds_read_b128 v[4:7], v144
	ds_read_b128 v[8:11], v144 offset:1024
	ds_read_b128 v[140:143], v144 offset:2048
	ds_read_b128 v[144:147], v144 offset:3072
	ds_read_b128 v[172:175], v160
	ds_read_b128 v[176:179], v160 offset:1024
	ds_read_b128 v[180:183], v160 offset:2048
	ds_read_b128 v[184:187], v160 offset:3072
	s_add_i32 m0, s13, 0xc000
	ds_read_b128 v[188:191], v170
	ds_read_b128 v[192:195], v170 offset:1024
	ds_read_b128 v[196:199], v170 offset:2048
	ds_read_b128 v[200:203], v170 offset:3072
	ds_read_b128 v[204:207], v170 offset:4096
	ds_read_b128 v[212:215], v170 offset:5120
	ds_read_b128 v[216:219], v170 offset:6144
	ds_read_b128 v[220:223], v170 offset:7168
	global_load_lds_dwordx4 v156, s[22:23]
	s_add_i32 m0, s13, 0xe000
	s_nop 0
	global_load_lds_dwordx4 v158, s[22:23]
	s_waitcnt vmcnt(8)
	s_waitcnt lgkmcnt(0)
	s_barrier
	s_setprio 1
	s_waitcnt lgkmcnt(0)
	v_mfma_f32_16x16x32_bf16 v[136:139], v[4:7], v[188:191], v[136:139]
	v_mfma_f32_16x16x32_bf16 v[132:135], v[140:143], v[188:191], v[132:135]
	v_mfma_f32_16x16x32_bf16 v[128:131], v[4:7], v[196:199], v[128:131]
	v_mfma_f32_16x16x32_bf16 v[120:123], v[140:143], v[196:199], v[120:123]
	v_mfma_f32_16x16x32_bf16 v[112:115], v[4:7], v[204:207], v[112:115]
	v_mfma_f32_16x16x32_bf16 v[104:107], v[140:143], v[204:207], v[104:107]
	v_mfma_f32_16x16x32_bf16 v[96:99], v[4:7], v[216:219], v[96:99]
	v_mfma_f32_16x16x32_bf16 v[88:91], v[140:143], v[216:219], v[88:91]
	v_mfma_f32_16x16x32_bf16 v[136:139], v[8:11], v[192:195], v[136:139]
	v_mfma_f32_16x16x32_bf16 v[132:135], v[144:147], v[192:195], v[132:135]
	v_mfma_f32_16x16x32_bf16 v[128:131], v[8:11], v[200:203], v[128:131]
	v_mfma_f32_16x16x32_bf16 v[120:123], v[144:147], v[200:203], v[120:123]
	v_mfma_f32_16x16x32_bf16 v[112:115], v[8:11], v[212:215], v[112:115]
	v_mfma_f32_16x16x32_bf16 v[104:107], v[144:147], v[212:215], v[104:107]
	v_mfma_f32_16x16x32_bf16 v[96:99], v[8:11], v[220:223], v[96:99]
	v_mfma_f32_16x16x32_bf16 v[88:91], v[144:147], v[220:223], v[88:91]
	s_setprio 0
	s_setprio 1
	v_mfma_f32_16x16x32_bf16 v[124:127], v[172:175], v[188:191], v[124:127]
	v_mfma_f32_16x16x32_bf16 v[116:119], v[180:183], v[188:191], v[116:119]
	v_mfma_f32_16x16x32_bf16 v[108:111], v[172:175], v[196:199], v[108:111]
	v_mfma_f32_16x16x32_bf16 v[100:103], v[180:183], v[196:199], v[100:103]
	v_mfma_f32_16x16x32_bf16 v[92:95], v[172:175], v[204:207], v[92:95]
	v_mfma_f32_16x16x32_bf16 v[84:87], v[180:183], v[204:207], v[84:87]
	v_mfma_f32_16x16x32_bf16 v[80:83], v[172:175], v[216:219], v[80:83]
	v_mfma_f32_16x16x32_bf16 v[76:79], v[180:183], v[216:219], v[76:79]
	v_mfma_f32_16x16x32_bf16 v[124:127], v[176:179], v[192:195], v[124:127]
	v_mfma_f32_16x16x32_bf16 v[116:119], v[184:187], v[192:195], v[116:119]
	v_mfma_f32_16x16x32_bf16 v[108:111], v[176:179], v[200:203], v[108:111]
	v_mfma_f32_16x16x32_bf16 v[100:103], v[184:187], v[200:203], v[100:103]
	v_mfma_f32_16x16x32_bf16 v[92:95], v[176:179], v[212:215], v[92:95]
	v_mfma_f32_16x16x32_bf16 v[84:87], v[184:187], v[212:215], v[84:87]
	v_mfma_f32_16x16x32_bf16 v[80:83], v[176:179], v[220:223], v[80:83]
	v_mfma_f32_16x16x32_bf16 v[76:79], v[184:187], v[220:223], v[76:79]
	s_setprio 0
	s_barrier
	s_add_i32 s34, s34, s7
	s_add_u32 s98, s26, 0x80
	s_addc_u32 s99, s27, 0
	s_add_u32 s100, s38, 0x800
	s_addc_u32 s101, s39, 0
	s_mov_b32 m0, s34
	ds_read_b128 v[188:191], v170 offset:16384
	ds_read_b128 v[192:195], v170 offset:17408
	ds_read_b128 v[196:199], v170 offset:18432
	ds_read_b128 v[200:203], v170 offset:19456
	ds_read_b128 v[204:207], v170 offset:20480
	ds_read_b128 v[212:215], v170 offset:21504
	ds_read_b128 v[216:219], v170 offset:22528
	ds_read_b128 v[220:223], v170 offset:23552
	global_load_lds_dwordx4 v2, s[26:27]
	s_add_i32 m0, s34, 0x2000
	s_add_u32 s34, s26, 0x80000
	s_addc_u32 s35, s27, 0
	s_add_i32 s53, s53, s7
	global_load_lds_dwordx4 v148, s[26:27]
	s_mov_b32 m0, s53
	s_nop 0
	global_load_lds_dwordx4 v2, s[34:35]
	s_add_i32 m0, s53, 0x2000
	s_nop 0
	global_load_lds_dwordx4 v148, s[34:35]
	s_mov_b32 m0, s13
	s_nop 0
	global_load_lds_dwordx4 v152, s[38:39]
	s_mov_b32 m0, s46
	s_nop 0
	global_load_lds_dwordx4 v150, s[38:39]
	s_waitcnt vmcnt(8)
	s_waitcnt lgkmcnt(0)
	s_barrier
	s_setprio 1
	s_waitcnt lgkmcnt(0)
	v_mfma_f32_16x16x32_bf16 v[72:75], v[4:7], v[188:191], v[72:75]
	v_mfma_f32_16x16x32_bf16 v[68:71], v[140:143], v[188:191], v[68:71]
	v_mfma_f32_16x16x32_bf16 v[64:67], v[4:7], v[196:199], v[64:67]
	v_mfma_f32_16x16x32_bf16 v[56:59], v[140:143], v[196:199], v[56:59]
	v_mfma_f32_16x16x32_bf16 v[48:51], v[4:7], v[204:207], v[48:51]
	v_mfma_f32_16x16x32_bf16 v[40:43], v[140:143], v[204:207], v[40:43]
	v_mfma_f32_16x16x32_bf16 v[4:7], v[4:7], v[216:219], v[32:35]
	v_mfma_f32_16x16x32_bf16 v[72:75], v[8:11], v[192:195], v[72:75]
	v_mfma_f32_16x16x32_bf16 v[68:71], v[144:147], v[192:195], v[68:71]
	v_mfma_f32_16x16x32_bf16 v[64:67], v[8:11], v[200:203], v[64:67]
	v_mfma_f32_16x16x32_bf16 v[56:59], v[144:147], v[200:203], v[56:59]
	v_mfma_f32_16x16x32_bf16 v[48:51], v[8:11], v[212:215], v[48:51]
	v_mfma_f32_16x16x32_bf16 v[40:43], v[144:147], v[212:215], v[40:43]
	v_mfma_f32_16x16x32_bf16 v[4:7], v[8:11], v[220:223], v[4:7]
	v_mfma_f32_16x16x32_bf16 v[8:11], v[140:143], v[216:219], v[24:27]
	v_mfma_f32_16x16x32_bf16 v[8:11], v[144:147], v[220:223], v[8:11]
	s_setprio 0
	s_setprio 1
	v_mfma_f32_16x16x32_bf16 v[24:27], v[172:175], v[188:191], v[60:63]
	v_mfma_f32_16x16x32_bf16 v[60:63], v[176:179], v[192:195], v[24:27]
	v_mfma_f32_16x16x32_bf16 v[24:27], v[180:183], v[188:191], v[52:55]
	v_mfma_f32_16x16x32_bf16 v[52:55], v[184:187], v[192:195], v[24:27]
	v_mfma_f32_16x16x32_bf16 v[24:27], v[172:175], v[196:199], v[44:47]
	v_mfma_f32_16x16x32_bf16 v[44:47], v[176:179], v[200:203], v[24:27]
	v_mfma_f32_16x16x32_bf16 v[24:27], v[180:183], v[196:199], v[36:39]
	v_mfma_f32_16x16x32_bf16 v[36:39], v[184:187], v[200:203], v[24:27]
	v_mfma_f32_16x16x32_bf16 v[24:27], v[172:175], v[204:207], v[28:31]
	v_mfma_f32_16x16x32_bf16 v[20:23], v[180:183], v[204:207], v[20:23]
	v_mfma_f32_16x16x32_bf16 v[16:19], v[172:175], v[216:219], v[16:19]
	v_mfma_f32_16x16x32_bf16 v[12:15], v[180:183], v[216:219], v[12:15]
	v_mfma_f32_16x16x32_bf16 v[28:31], v[176:179], v[212:215], v[24:27]
	v_mfma_f32_16x16x32_bf16 v[20:23], v[184:187], v[212:215], v[20:23]
	v_mfma_f32_16x16x32_bf16 v[16:19], v[176:179], v[220:223], v[16:19]
	v_mfma_f32_16x16x32_bf16 v[12:15], v[184:187], v[220:223], v[12:15]
	s_setprio 0
	s_barrier
	s_add_i32 s53, 0, 0x18000
	s_add_i32 s54, 0, 0x1c000
	v_add_u32_e32 v144, s53, v168
	v_add_u32_e32 v171, s54, v168
	ds_read_b128 v[24:27], v144
	ds_read_b128 v[32:35], v144 offset:1024
	ds_read_b128 v[140:143], v144 offset:2048
	ds_read_b128 v[144:147], v144 offset:3072
	ds_read_b128 v[172:175], v171
	ds_read_b128 v[176:179], v171 offset:1024
	ds_read_b128 v[180:183], v171 offset:2048
	ds_read_b128 v[184:187], v171 offset:3072
	s_add_u32 s34, s38, 0x80000
	s_addc_u32 s35, s39, 0
	s_mov_b32 m0, s47
	ds_read_b128 v[188:191], v170 offset:32768
	ds_read_b128 v[192:195], v170 offset:33792
	ds_read_b128 v[196:199], v170 offset:34816
	ds_read_b128 v[200:203], v170 offset:35840
	ds_read_b128 v[204:207], v170 offset:36864
	ds_read_b128 v[212:215], v170 offset:37888
	ds_read_b128 v[216:219], v170 offset:38912
	ds_read_b128 v[220:223], v170 offset:39936
	global_load_lds_dwordx4 v152, s[34:35]
	s_mov_b32 m0, s48
	s_nop 0
	global_load_lds_dwordx4 v150, s[34:35]
	s_waitcnt vmcnt(8)
	s_waitcnt lgkmcnt(0)
	s_barrier
	s_setprio 1
	s_waitcnt lgkmcnt(0)
	v_mfma_f32_16x16x32_bf16 v[136:139], v[24:27], v[188:191], v[136:139]
	v_mfma_f32_16x16x32_bf16 v[132:135], v[140:143], v[188:191], v[132:135]
	v_mfma_f32_16x16x32_bf16 v[128:131], v[24:27], v[196:199], v[128:131]
	v_mfma_f32_16x16x32_bf16 v[120:123], v[140:143], v[196:199], v[120:123]
	v_mfma_f32_16x16x32_bf16 v[112:115], v[24:27], v[204:207], v[112:115]
	v_mfma_f32_16x16x32_bf16 v[104:107], v[140:143], v[204:207], v[104:107]
	v_mfma_f32_16x16x32_bf16 v[96:99], v[24:27], v[216:219], v[96:99]
	v_mfma_f32_16x16x32_bf16 v[88:91], v[140:143], v[216:219], v[88:91]
	v_mfma_f32_16x16x32_bf16 v[136:139], v[32:35], v[192:195], v[136:139]
	v_mfma_f32_16x16x32_bf16 v[132:135], v[144:147], v[192:195], v[132:135]
	v_mfma_f32_16x16x32_bf16 v[128:131], v[32:35], v[200:203], v[128:131]
	v_mfma_f32_16x16x32_bf16 v[120:123], v[144:147], v[200:203], v[120:123]
	v_mfma_f32_16x16x32_bf16 v[112:115], v[32:35], v[212:215], v[112:115]
	v_mfma_f32_16x16x32_bf16 v[104:107], v[144:147], v[212:215], v[104:107]
	v_mfma_f32_16x16x32_bf16 v[96:99], v[32:35], v[220:223], v[96:99]
	v_mfma_f32_16x16x32_bf16 v[88:91], v[144:147], v[220:223], v[88:91]
	s_setprio 0
	s_setprio 1
	v_mfma_f32_16x16x32_bf16 v[124:127], v[172:175], v[188:191], v[124:127]
	v_mfma_f32_16x16x32_bf16 v[116:119], v[180:183], v[188:191], v[116:119]
	v_mfma_f32_16x16x32_bf16 v[108:111], v[172:175], v[196:199], v[108:111]
	v_mfma_f32_16x16x32_bf16 v[100:103], v[180:183], v[196:199], v[100:103]
	v_mfma_f32_16x16x32_bf16 v[92:95], v[172:175], v[204:207], v[92:95]
	v_mfma_f32_16x16x32_bf16 v[84:87], v[180:183], v[204:207], v[84:87]
	v_mfma_f32_16x16x32_bf16 v[80:83], v[172:175], v[216:219], v[80:83]
	v_mfma_f32_16x16x32_bf16 v[76:79], v[180:183], v[216:219], v[76:79]
	v_mfma_f32_16x16x32_bf16 v[124:127], v[176:179], v[192:195], v[124:127]
	v_mfma_f32_16x16x32_bf16 v[116:119], v[184:187], v[192:195], v[116:119]
	v_mfma_f32_16x16x32_bf16 v[108:111], v[176:179], v[200:203], v[108:111]
	v_mfma_f32_16x16x32_bf16 v[100:103], v[184:187], v[200:203], v[100:103]
	v_mfma_f32_16x16x32_bf16 v[92:95], v[176:179], v[212:215], v[92:95]
	v_mfma_f32_16x16x32_bf16 v[84:87], v[184:187], v[212:215], v[84:87]
	v_mfma_f32_16x16x32_bf16 v[80:83], v[176:179], v[220:223], v[80:83]
	v_mfma_f32_16x16x32_bf16 v[76:79], v[184:187], v[220:223], v[76:79]
	s_setprio 0
	s_barrier
	s_add_i32 s34, s53, s7
	s_mov_b32 m0, s34
	ds_read_b128 v[188:191], v170 offset:49152
	ds_read_b128 v[192:195], v170 offset:50176
	ds_read_b128 v[196:199], v170 offset:51200
	ds_read_b128 v[200:203], v170 offset:52224
	ds_read_b128 v[204:207], v170 offset:53248
	ds_read_b128 v[212:215], v170 offset:54272
	ds_read_b128 v[216:219], v170 offset:55296
	ds_read_b128 v[220:223], v170 offset:56320
	global_load_lds_dwordx4 v2, s[98:99]
	s_add_i32 m0, s34, 0x2000
	s_add_u32 s26, s26, 0x80080
	s_addc_u32 s27, s27, 0
	s_add_i32 s34, s54, s7
	global_load_lds_dwordx4 v148, s[98:99]
	s_mov_b32 m0, s34
	s_nop 0
	global_load_lds_dwordx4 v2, s[26:27]
	s_add_i32 m0, s34, 0x2000
	s_nop 0
	global_load_lds_dwordx4 v148, s[26:27]
	s_mov_b32 m0, s49
	s_nop 0
	global_load_lds_dwordx4 v152, s[100:101]
	s_mov_b32 m0, s50
	s_nop 0
	global_load_lds_dwordx4 v150, s[100:101]
	s_waitcnt vmcnt(8)
	s_waitcnt lgkmcnt(0)
	s_barrier
	s_setprio 1
	s_waitcnt lgkmcnt(0)
	v_mfma_f32_16x16x32_bf16 v[72:75], v[24:27], v[188:191], v[72:75]
	v_mfma_f32_16x16x32_bf16 v[64:67], v[24:27], v[196:199], v[64:67]
	v_mfma_f32_16x16x32_bf16 v[48:51], v[24:27], v[204:207], v[48:51]
	v_mfma_f32_16x16x32_bf16 v[4:7], v[24:27], v[216:219], v[4:7]
	v_mfma_f32_16x16x32_bf16 v[72:75], v[32:35], v[192:195], v[72:75]
	v_mfma_f32_16x16x32_bf16 v[68:71], v[140:143], v[188:191], v[68:71]
	v_mfma_f32_16x16x32_bf16 v[64:67], v[32:35], v[200:203], v[64:67]
	v_mfma_f32_16x16x32_bf16 v[56:59], v[140:143], v[196:199], v[56:59]
	v_mfma_f32_16x16x32_bf16 v[48:51], v[32:35], v[212:215], v[48:51]
	v_mfma_f32_16x16x32_bf16 v[40:43], v[140:143], v[204:207], v[40:43]
	v_mfma_f32_16x16x32_bf16 v[32:35], v[32:35], v[220:223], v[4:7]
	v_mfma_f32_16x16x32_bf16 v[4:7], v[140:143], v[216:219], v[8:11]
	v_mfma_f32_16x16x32_bf16 v[68:71], v[144:147], v[192:195], v[68:71]
	v_mfma_f32_16x16x32_bf16 v[56:59], v[144:147], v[200:203], v[56:59]
	v_mfma_f32_16x16x32_bf16 v[40:43], v[144:147], v[212:215], v[40:43]
	v_mfma_f32_16x16x32_bf16 v[24:27], v[144:147], v[220:223], v[4:7]
	s_setprio 0
	s_setprio 1
	v_mfma_f32_16x16x32_bf16 v[4:7], v[172:175], v[188:191], v[60:63]
	v_mfma_f32_16x16x32_bf16 v[60:63], v[176:179], v[192:195], v[4:7]
	v_mfma_f32_16x16x32_bf16 v[4:7], v[180:183], v[188:191], v[52:55]
	v_mfma_f32_16x16x32_bf16 v[52:55], v[184:187], v[192:195], v[4:7]
	v_mfma_f32_16x16x32_bf16 v[4:7], v[172:175], v[196:199], v[44:47]
	v_mfma_f32_16x16x32_bf16 v[44:47], v[176:179], v[200:203], v[4:7]
	v_mfma_f32_16x16x32_bf16 v[4:7], v[180:183], v[196:199], v[36:39]
	v_mfma_f32_16x16x32_bf16 v[36:39], v[184:187], v[200:203], v[4:7]
	v_mfma_f32_16x16x32_bf16 v[4:7], v[172:175], v[204:207], v[28:31]
	v_mfma_f32_16x16x32_bf16 v[28:31], v[176:179], v[212:215], v[4:7]
	v_mfma_f32_16x16x32_bf16 v[4:7], v[180:183], v[204:207], v[20:23]
	v_mfma_f32_16x16x32_bf16 v[20:23], v[184:187], v[212:215], v[4:7]
	v_mfma_f32_16x16x32_bf16 v[4:7], v[172:175], v[216:219], v[16:19]
	v_mfma_f32_16x16x32_bf16 v[16:19], v[176:179], v[220:223], v[4:7]
	v_mfma_f32_16x16x32_bf16 v[4:7], v[180:183], v[216:219], v[12:15]
	v_mfma_f32_16x16x32_bf16 v[12:15], v[184:187], v[220:223], v[4:7]
	s_setprio 0
	s_barrier
	s_add_i32 s33, s33, 2
	s_add_u32 s22, s22, 0x1000
	s_addc_u32 s23, s23, 0
	s_add_u32 s15, s15, 0x100
	s_addc_u32 s17, s17, 0
	s_cmp_gt_u32 s33, 29
	s_cbranch_scc0 .LBB0_489
	s_and_b64 vcc, exec, s[4:5]
	s_cbranch_vccz .LBB0_492
	s_barrier

.LBB0_835:
	v_and_b32_e32 v153, 64, v208
	v_xor_b32_e32 v152, 16, v208
	v_add_u32_e32 v154, 64, v153
	v_cmp_lt_i32_e32 vcc, v152, v154
	v_lshl_add_u32 v151, s6, 8, v146
	v_lshl_or_b32 v2, s17, 9, v149
	v_readlane_b32 s2, v254, 39
	v_cndmask_b32_e32 v152, v208, v152, vcc
	v_lshl_add_u32 v2, v151, 12, v2
	v_and_b32_e32 v228, -16, v151
	v_lshlrev_b32_e32 v228, 12, v228
	v_lshrrev_b32_e32 v229, 6, v149
	v_lshlrev_b32_e32 v229, 10, v229
	v_lshl_or_b32 v229, s17, 13, v229
	v_and_b32_e32 v230, 15, v151
	v_lshl_or_b32 v229, v230, 6, v229
	v_bfe_u32 v230, v149, 4, 2
	v_lshrrev_b32_e32 v231, 2, v151
	v_and_b32_e32 v231, 2, v231
	v_xor_b32_e32 v230, v230, v231
	v_lshl_or_b32 v229, v230, 4, v229
	v_add_u32_e32 v229, 0x800, v229
	v_add_u32_e32 v2, v228, v229
	v_readlane_b32 s3, v254, 40
	v_lshlrev_b32_e32 v153, 2, v152
	v_xor_b32_e32 v152, 32, v208
	v_cmp_lt_i32_e32 vcc, v152, v154
	s_nop 1
	global_load_dwordx4 v[154:157], v2, s[2:3] offset:-2048
	global_load_dwordx4 v[158:161], v2, s[2:3] offset:2048
	v_lshl_add_u64 v[144:145], s[2:3], 0, v[2:3]
	v_cndmask_b32_e32 v152, v208, v152, vcc
	v_lshlrev_b32_e32 v152, 2, v152
	s_mov_b32 s99, 0
	s_mov_b32 s98, 0x10000
	v_lshl_add_u64 v[228:229], v[144:145], 0, s[98:99]
	global_load_dwordx4 v[168:171], v[228:229], off offset:2048
	global_load_dwordx4 v[172:175], v[228:229], off offset:-2048
	s_mov_b32 s98, 0x20000
	v_lshl_add_u64 v[230:231], v[144:145], 0, s[98:99]
	global_load_dwordx4 v[176:179], v[230:231], off offset:2048
	global_load_dwordx4 v[180:183], v[230:231], off offset:-2048
	s_mov_b32 s98, 0x30000
	v_lshl_add_u64 v[232:233], v[144:145], 0, s[98:99]
	global_load_dwordx4 v[184:187], v[232:233], off offset:2048
	global_load_dwordx4 v[188:191], v[232:233], off offset:-2048
	s_mov_b32 s98, 0x80000
	v_lshl_add_u64 v[234:235], v[144:145], 0, s[98:99]
	global_load_dwordx4 v[192:195], v[234:235], off offset:-2048
	global_load_dwordx4 v[196:199], v[234:235], off offset:2048
	s_mov_b32 s98, 0x90000
	v_lshl_add_u64 v[236:237], v[144:145], 0, s[98:99]
	global_load_dwordx4 v[200:203], v[236:237], off offset:2048
	global_load_dwordx4 v[204:207], v[236:237], off offset:-2048
	s_mov_b32 s98, 0xa0000
	v_lshl_add_u64 v[238:239], v[144:145], 0, s[98:99]
	global_load_dwordx4 v[212:215], v[238:239], off offset:2048
	global_load_dwordx4 v[216:219], v[238:239], off offset:-2048
	s_mov_b32 s98, 0xb0000
	v_lshl_add_u64 v[240:241], v[144:145], 0, s[98:99]
	global_load_dwordx4 v[220:223], v[240:241], off offset:2048
	global_load_dwordx4 v[224:227], v[240:241], off offset:-2048
	s_waitcnt vmcnt(14)
	v_lshlrev_b32_e32 v162, 16, v154
	v_and_b32_e32 v163, 0xffff0000, v154
	v_pk_fma_f32 v[162:163], v[128:129], s[14:15], v[162:163]
	v_lshlrev_b32_e32 v154, 16, v155
	v_cvt_pk_bf16_f32 v128, v162, v163
	v_fma_f32 v162, v162, v162, 0
	v_and_b32_e32 v155, 0xffff0000, v155
	v_fmac_f32_e32 v162, v163, v163
	v_pk_fma_f32 v[130:131], v[130:131], s[14:15], v[154:155]
	s_nop 0
	v_fmac_f32_e32 v162, v130, v130
	v_cvt_pk_bf16_f32 v129, v130, v131
	v_fmac_f32_e32 v162, v131, v131
	v_lshlrev_b32_e32 v130, 16, v156
	v_and_b32_e32 v131, 0xffff0000, v156
	v_pk_fma_f32 v[124:125], v[124:125], s[14:15], v[130:131]
	s_nop 0
	v_fmac_f32_e32 v162, v124, v124
	v_cvt_pk_bf16_f32 v130, v124, v125
	v_fmac_f32_e32 v162, v125, v125
	v_lshlrev_b32_e32 v124, 16, v157
	v_and_b32_e32 v125, 0xffff0000, v157
	v_pk_fma_f32 v[124:125], v[126:127], s[14:15], v[124:125]
	s_nop 0
	v_fmac_f32_e32 v162, v124, v124
	v_cvt_pk_bf16_f32 v131, v124, v125
	v_fmac_f32_e32 v162, v125, v125
	v_lshlrev_b32_e32 v124, 16, v158
	v_and_b32_e32 v125, 0xffff0000, v158
	v_pk_fma_f32 v[124:125], v[120:121], s[14:15], v[124:125]
	s_nop 0
	v_fmac_f32_e32 v162, v124, v124
	v_cvt_pk_bf16_f32 v120, v124, v125
	v_fmac_f32_e32 v162, v125, v125
	v_lshlrev_b32_e32 v124, 16, v159
	v_and_b32_e32 v125, 0xffff0000, v159
	v_pk_fma_f32 v[122:123], v[122:123], s[14:15], v[124:125]
	s_nop 0
	v_fmac_f32_e32 v162, v122, v122
	v_cvt_pk_bf16_f32 v121, v122, v123
	v_fmac_f32_e32 v162, v123, v123
	v_lshlrev_b32_e32 v122, 16, v160
	v_and_b32_e32 v123, 0xffff0000, v160
	v_pk_fma_f32 v[116:117], v[116:117], s[14:15], v[122:123]
	s_nop 0
	v_fmac_f32_e32 v162, v116, v116
	v_cvt_pk_bf16_f32 v122, v116, v117
	v_fmac_f32_e32 v162, v117, v117
	v_lshlrev_b32_e32 v116, 16, v161
	v_and_b32_e32 v117, 0xffff0000, v161
	v_pk_fma_f32 v[116:117], v[118:119], s[14:15], v[116:117]
	s_nop 0
	v_fmac_f32_e32 v162, v116, v116
	v_fmac_f32_e32 v162, v117, v117
	v_cvt_pk_bf16_f32 v123, v116, v117
	global_store_dwordx4 v2, v[128:131], s[2:3] offset:-2048
	global_store_dwordx4 v2, v[120:123], s[2:3] offset:2048
	ds_bpermute_b32 v2, v153, v162
	s_mov_b32 s2, 0x10000
	v_add_co_u32_e32 v124, vcc, s2, v144
	s_mov_b32 s2, 0x20000
	s_waitcnt lgkmcnt(0)
	v_add_f32_e32 v2, v162, v2
	ds_bpermute_b32 v116, v152, v2
	v_addc_co_u32_e32 v125, vcc, 0, v145, vcc
	s_waitcnt lgkmcnt(0)
	v_add_f32_e32 v2, v2, v116
	s_waitcnt vmcnt(14)
	v_lshlrev_b32_e32 v126, 16, v172
	v_and_b32_e32 v127, 0xffff0000, v172
	v_pk_fma_f32 v[126:127], v[112:113], s[14:15], v[126:127]
	v_lshlrev_b32_e32 v120, 16, v173
	v_cvt_pk_bf16_f32 v112, v126, v127
	v_fma_f32 v126, v126, v126, 0
	v_and_b32_e32 v121, 0xffff0000, v173
	v_fmac_f32_e32 v126, v127, v127
	v_pk_fma_f32 v[114:115], v[114:115], s[14:15], v[120:121]
	s_nop 0
	v_fmac_f32_e32 v126, v114, v114
	v_cvt_pk_bf16_f32 v113, v114, v115
	v_fmac_f32_e32 v126, v115, v115
	v_lshlrev_b32_e32 v114, 16, v174
	v_and_b32_e32 v115, 0xffff0000, v174
	v_pk_fma_f32 v[108:109], v[108:109], s[14:15], v[114:115]
	s_nop 0
	v_fmac_f32_e32 v126, v108, v108
	v_cvt_pk_bf16_f32 v114, v108, v109
	v_fmac_f32_e32 v126, v109, v109
	v_lshlrev_b32_e32 v108, 16, v175
	v_and_b32_e32 v109, 0xffff0000, v175
	v_pk_fma_f32 v[108:109], v[110:111], s[14:15], v[108:109]
	v_add_co_u32_e32 v110, vcc, s2, v144
	v_fmac_f32_e32 v126, v108, v108
	v_cvt_pk_bf16_f32 v115, v108, v109
	v_fmac_f32_e32 v126, v109, v109
	v_lshlrev_b32_e32 v108, 16, v168
	v_and_b32_e32 v109, 0xffff0000, v168
	v_pk_fma_f32 v[108:109], v[104:105], s[14:15], v[108:109]
	v_addc_co_u32_e32 v111, vcc, 0, v145, vcc
	v_fmac_f32_e32 v126, v108, v108
	v_cvt_pk_bf16_f32 v104, v108, v109
	v_fmac_f32_e32 v126, v109, v109
	v_lshlrev_b32_e32 v108, 16, v169
	v_and_b32_e32 v109, 0xffff0000, v169
	v_pk_fma_f32 v[106:107], v[106:107], s[14:15], v[108:109]
	s_mov_b32 s2, 0x30000
	v_fmac_f32_e32 v126, v106, v106
	v_cvt_pk_bf16_f32 v105, v106, v107
	v_fmac_f32_e32 v126, v107, v107
	v_lshlrev_b32_e32 v106, 16, v170
	v_and_b32_e32 v107, 0xffff0000, v170
	v_pk_fma_f32 v[100:101], v[100:101], s[14:15], v[106:107]
	s_nop 0
	v_fmac_f32_e32 v126, v100, v100
	v_cvt_pk_bf16_f32 v106, v100, v101
	v_fmac_f32_e32 v126, v101, v101
	v_lshlrev_b32_e32 v100, 16, v171
	v_and_b32_e32 v101, 0xffff0000, v171
	v_pk_fma_f32 v[100:101], v[102:103], s[14:15], v[100:101]
	s_nop 0
	v_cvt_pk_bf16_f32 v107, v100, v101
	global_store_dwordx4 v[124:125], v[112:115], off offset:-2048
	global_store_dwordx4 v[124:125], v[104:107], off offset:2048
	s_nop 0
	v_fmac_f32_e32 v126, v100, v100
	v_fmac_f32_e32 v126, v101, v101
	ds_bpermute_b32 v100, v153, v126
	s_waitcnt lgkmcnt(0)
	v_add_f32_e32 v100, v126, v100
	ds_bpermute_b32 v101, v152, v100
	s_waitcnt vmcnt(14)
	v_lshlrev_b32_e32 v112, 16, v180
	v_and_b32_e32 v113, 0xffff0000, v180
	v_pk_fma_f32 v[112:113], v[96:97], s[14:15], v[112:113]
	v_lshlrev_b32_e32 v106, 16, v181
	v_cvt_pk_bf16_f32 v96, v112, v113
	v_fma_f32 v112, v112, v112, 0
	v_and_b32_e32 v107, 0xffff0000, v181
	v_fmac_f32_e32 v112, v113, v113
	v_pk_fma_f32 v[98:99], v[98:99], s[14:15], v[106:107]
	s_nop 0
	v_fmac_f32_e32 v112, v98, v98
	v_cvt_pk_bf16_f32 v97, v98, v99
	v_fmac_f32_e32 v112, v99, v99
	v_lshlrev_b32_e32 v98, 16, v182
	v_and_b32_e32 v99, 0xffff0000, v182
	v_pk_fma_f32 v[92:93], v[92:93], s[14:15], v[98:99]
	s_nop 0
	v_fmac_f32_e32 v112, v92, v92
	v_cvt_pk_bf16_f32 v98, v92, v93
	v_fmac_f32_e32 v112, v93, v93
	v_lshlrev_b32_e32 v92, 16, v183
	v_and_b32_e32 v93, 0xffff0000, v183
	v_pk_fma_f32 v[92:93], v[94:95], s[14:15], v[92:93]
	s_nop 0
	v_fmac_f32_e32 v112, v92, v92
	v_cvt_pk_bf16_f32 v99, v92, v93
	v_fmac_f32_e32 v112, v93, v93
	v_lshlrev_b32_e32 v92, 16, v176
	v_and_b32_e32 v93, 0xffff0000, v176
	v_pk_fma_f32 v[92:93], v[88:89], s[14:15], v[92:93]
	s_nop 0
	v_fmac_f32_e32 v112, v92, v92
	v_cvt_pk_bf16_f32 v88, v92, v93
	v_fmac_f32_e32 v112, v93, v93
	v_lshlrev_b32_e32 v92, 16, v177
	v_and_b32_e32 v93, 0xffff0000, v177
	v_pk_fma_f32 v[90:91], v[90:91], s[14:15], v[92:93]
	v_add_co_u32_e32 v92, vcc, s2, v144
	v_fmac_f32_e32 v112, v90, v90
	v_cvt_pk_bf16_f32 v89, v90, v91
	v_fmac_f32_e32 v112, v91, v91
	v_lshlrev_b32_e32 v90, 16, v178
	v_and_b32_e32 v91, 0xffff0000, v178
	v_pk_fma_f32 v[84:85], v[84:85], s[14:15], v[90:91]
	v_addc_co_u32_e32 v93, vcc, 0, v145, vcc
	v_fmac_f32_e32 v112, v84, v84
	v_cvt_pk_bf16_f32 v90, v84, v85
	v_fmac_f32_e32 v112, v85, v85
	v_lshlrev_b32_e32 v84, 16, v179
	v_and_b32_e32 v85, 0xffff0000, v179
	v_pk_fma_f32 v[84:85], v[86:87], s[14:15], v[84:85]
	s_mov_b32 s2, 0x80000
	v_fmac_f32_e32 v112, v84, v84
	v_fmac_f32_e32 v112, v85, v85
	v_cvt_pk_bf16_f32 v91, v84, v85
	ds_bpermute_b32 v84, v153, v112
	global_store_dwordx4 v[110:111], v[96:99], off offset:-2048
	global_store_dwordx4 v[110:111], v[88:91], off offset:2048
	s_waitcnt lgkmcnt(0)
	v_add_f32_e32 v94, v112, v84
	ds_bpermute_b32 v95, v152, v94
	s_waitcnt vmcnt(14)
	v_lshlrev_b32_e32 v96, 16, v188
	v_and_b32_e32 v97, 0xffff0000, v188
	v_pk_fma_f32 v[96:97], v[80:81], s[14:15], v[96:97]
	v_lshlrev_b32_e32 v88, 16, v189
	v_cvt_pk_bf16_f32 v80, v96, v97
	v_fma_f32 v96, v96, v96, 0
	v_and_b32_e32 v89, 0xffff0000, v189
	v_fmac_f32_e32 v96, v97, v97
	v_pk_fma_f32 v[82:83], v[82:83], s[14:15], v[88:89]
	s_nop 0
	v_fmac_f32_e32 v96, v82, v82
	v_cvt_pk_bf16_f32 v81, v82, v83
	v_fmac_f32_e32 v96, v83, v83
	v_lshlrev_b32_e32 v82, 16, v190
	v_and_b32_e32 v83, 0xffff0000, v190
	v_pk_fma_f32 v[76:77], v[76:77], s[14:15], v[82:83]
	s_nop 0
	v_fmac_f32_e32 v96, v76, v76
	v_cvt_pk_bf16_f32 v82, v76, v77
	v_fmac_f32_e32 v96, v77, v77
	v_lshlrev_b32_e32 v76, 16, v191
	v_and_b32_e32 v77, 0xffff0000, v191
	v_pk_fma_f32 v[76:77], v[78:79], s[14:15], v[76:77]
	v_add_co_u32_e32 v78, vcc, s2, v144
	v_fmac_f32_e32 v96, v76, v76
	v_cvt_pk_bf16_f32 v83, v76, v77
	v_fmac_f32_e32 v96, v77, v77
	v_lshlrev_b32_e32 v76, 16, v184
	v_and_b32_e32 v77, 0xffff0000, v184
	v_pk_fma_f32 v[76:77], v[72:73], s[14:15], v[76:77]
	v_addc_co_u32_e32 v79, vcc, 0, v145, vcc
	v_fmac_f32_e32 v96, v76, v76
	v_cvt_pk_bf16_f32 v72, v76, v77
	v_fmac_f32_e32 v96, v77, v77
	v_lshlrev_b32_e32 v76, 16, v185
	v_and_b32_e32 v77, 0xffff0000, v185
	v_pk_fma_f32 v[74:75], v[74:75], s[14:15], v[76:77]
	s_mov_b32 s2, 0x90000
	v_fmac_f32_e32 v96, v74, v74
	v_cvt_pk_bf16_f32 v73, v74, v75
	v_fmac_f32_e32 v96, v75, v75
	v_lshlrev_b32_e32 v74, 16, v186
	v_and_b32_e32 v75, 0xffff0000, v186
	v_pk_fma_f32 v[68:69], v[68:69], s[14:15], v[74:75]
	s_nop 0
	v_fmac_f32_e32 v96, v68, v68
	v_cvt_pk_bf16_f32 v74, v68, v69
	v_fmac_f32_e32 v96, v69, v69
	v_lshlrev_b32_e32 v68, 16, v187
	v_and_b32_e32 v69, 0xffff0000, v187
	v_pk_fma_f32 v[68:69], v[70:71], s[14:15], v[68:69]
	s_nop 0
	v_cvt_pk_bf16_f32 v75, v68, v69
	global_store_dwordx4 v[92:93], v[80:83], off offset:-2048
	global_store_dwordx4 v[92:93], v[72:75], off offset:2048
	v_fmac_f32_e32 v96, v68, v68
	v_fmac_f32_e32 v96, v69, v69
	ds_bpermute_b32 v68, v153, v96
	s_waitcnt lgkmcnt(0)
	v_add_f32_e32 v68, v96, v68
	ds_bpermute_b32 v69, v152, v68
	s_waitcnt vmcnt(15)
	v_lshlrev_b32_e32 v80, 16, v192
	v_and_b32_e32 v81, 0xffff0000, v192
	v_pk_fma_f32 v[80:81], v[64:65], s[14:15], v[80:81]
	v_lshlrev_b32_e32 v70, 16, v193
	v_cvt_pk_bf16_f32 v64, v80, v81
	v_fma_f32 v80, v80, v80, 0
	v_and_b32_e32 v71, 0xffff0000, v193
	v_fmac_f32_e32 v80, v81, v81
	v_pk_fma_f32 v[66:67], v[66:67], s[14:15], v[70:71]
	s_nop 0
	v_fmac_f32_e32 v80, v66, v66
	v_cvt_pk_bf16_f32 v65, v66, v67
	v_fmac_f32_e32 v80, v67, v67
	v_lshlrev_b32_e32 v66, 16, v194
	v_and_b32_e32 v67, 0xffff0000, v194
	v_pk_fma_f32 v[60:61], v[60:61], s[14:15], v[66:67]
	s_nop 0
	v_fmac_f32_e32 v80, v60, v60
	v_cvt_pk_bf16_f32 v66, v60, v61
	v_fmac_f32_e32 v80, v61, v61
	v_lshlrev_b32_e32 v60, 16, v195
	v_and_b32_e32 v61, 0xffff0000, v195
	v_pk_fma_f32 v[60:61], v[62:63], s[14:15], v[60:61]
	v_add_co_u32_e32 v62, vcc, s2, v144
	v_fmac_f32_e32 v80, v60, v60
	v_cvt_pk_bf16_f32 v67, v60, v61
	v_fmac_f32_e32 v80, v61, v61
	s_waitcnt vmcnt(14)
	v_lshlrev_b32_e32 v60, 16, v196
	v_and_b32_e32 v61, 0xffff0000, v196
	v_pk_fma_f32 v[60:61], v[56:57], s[14:15], v[60:61]
	v_addc_co_u32_e32 v63, vcc, 0, v145, vcc
	v_fmac_f32_e32 v80, v60, v60
	v_cvt_pk_bf16_f32 v56, v60, v61
	v_fmac_f32_e32 v80, v61, v61
	v_lshlrev_b32_e32 v60, 16, v197
	v_and_b32_e32 v61, 0xffff0000, v197
	v_pk_fma_f32 v[58:59], v[58:59], s[14:15], v[60:61]
	s_mov_b32 s2, 0xa0000
	v_fmac_f32_e32 v80, v58, v58
	v_cvt_pk_bf16_f32 v57, v58, v59
	v_fmac_f32_e32 v80, v59, v59
	v_lshlrev_b32_e32 v58, 16, v198
	v_and_b32_e32 v59, 0xffff0000, v198
	v_pk_fma_f32 v[52:53], v[52:53], s[14:15], v[58:59]
	s_nop 0
	v_fmac_f32_e32 v80, v52, v52
	v_cvt_pk_bf16_f32 v58, v52, v53
	v_fmac_f32_e32 v80, v53, v53
	v_lshlrev_b32_e32 v52, 16, v199
	v_and_b32_e32 v53, 0xffff0000, v199
	v_pk_fma_f32 v[52:53], v[54:55], s[14:15], v[52:53]
	s_nop 0
	v_cvt_pk_bf16_f32 v59, v52, v53
	global_store_dwordx4 v[78:79], v[64:67], off offset:-2048
	global_store_dwordx4 v[78:79], v[56:59], off offset:2048
	s_nop 0
	v_fmac_f32_e32 v80, v52, v52
	v_fmac_f32_e32 v80, v53, v53
	ds_bpermute_b32 v52, v153, v80
	s_waitcnt lgkmcnt(0)
	v_add_f32_e32 v52, v80, v52
	ds_bpermute_b32 v53, v152, v52
	s_waitcnt vmcnt(14)
	v_lshlrev_b32_e32 v64, 16, v204
	v_and_b32_e32 v65, 0xffff0000, v204
	v_pk_fma_f32 v[64:65], v[48:49], s[14:15], v[64:65]
	v_lshlrev_b32_e32 v58, 16, v205
	v_cvt_pk_bf16_f32 v48, v64, v65
	v_fma_f32 v64, v64, v64, 0
	v_and_b32_e32 v59, 0xffff0000, v205
	v_fmac_f32_e32 v64, v65, v65
	v_pk_fma_f32 v[50:51], v[50:51], s[14:15], v[58:59]
	s_nop 0
	v_fmac_f32_e32 v64, v50, v50
	v_cvt_pk_bf16_f32 v49, v50, v51
	v_fmac_f32_e32 v64, v51, v51
	v_lshlrev_b32_e32 v50, 16, v206
	v_and_b32_e32 v51, 0xffff0000, v206
	v_pk_fma_f32 v[44:45], v[44:45], s[14:15], v[50:51]
	s_nop 0
	v_fmac_f32_e32 v64, v44, v44
	v_cvt_pk_bf16_f32 v50, v44, v45
	v_fmac_f32_e32 v64, v45, v45
	v_lshlrev_b32_e32 v44, 16, v207
	v_and_b32_e32 v45, 0xffff0000, v207
	v_pk_fma_f32 v[44:45], v[46:47], s[14:15], v[44:45]
	v_add_co_u32_e32 v46, vcc, s2, v144
	v_fmac_f32_e32 v64, v44, v44
	v_cvt_pk_bf16_f32 v51, v44, v45
	v_fmac_f32_e32 v64, v45, v45
	v_lshlrev_b32_e32 v44, 16, v200
	v_and_b32_e32 v45, 0xffff0000, v200
	v_pk_fma_f32 v[44:45], v[40:41], s[14:15], v[44:45]
	v_addc_co_u32_e32 v47, vcc, 0, v145, vcc
	v_fmac_f32_e32 v64, v44, v44
	v_cvt_pk_bf16_f32 v40, v44, v45
	v_fmac_f32_e32 v64, v45, v45
	v_lshlrev_b32_e32 v44, 16, v201
	v_and_b32_e32 v45, 0xffff0000, v201
	v_pk_fma_f32 v[42:43], v[42:43], s[14:15], v[44:45]
	s_mov_b32 s2, 0xb0000
	v_fmac_f32_e32 v64, v42, v42
	v_cvt_pk_bf16_f32 v41, v42, v43
	v_fmac_f32_e32 v64, v43, v43
	v_lshlrev_b32_e32 v42, 16, v202
	v_and_b32_e32 v43, 0xffff0000, v202
	v_pk_fma_f32 v[36:37], v[36:37], s[14:15], v[42:43]
	s_nop 0
	v_fmac_f32_e32 v64, v36, v36
	v_cvt_pk_bf16_f32 v42, v36, v37
	v_fmac_f32_e32 v64, v37, v37
	v_lshlrev_b32_e32 v36, 16, v203
	v_and_b32_e32 v37, 0xffff0000, v203
	v_pk_fma_f32 v[36:37], v[38:39], s[14:15], v[36:37]
	s_nop 0
	v_cvt_pk_bf16_f32 v43, v36, v37
	global_store_dwordx4 v[62:63], v[48:51], off offset:-2048
	global_store_dwordx4 v[62:63], v[40:43], off offset:2048
	s_nop 0
	v_fmac_f32_e32 v64, v36, v36
	v_fmac_f32_e32 v64, v37, v37
	ds_bpermute_b32 v36, v153, v64
	s_waitcnt lgkmcnt(0)
	v_add_f32_e32 v36, v64, v36
	ds_bpermute_b32 v37, v152, v36
	s_waitcnt vmcnt(14)
	v_lshlrev_b32_e32 v48, 16, v216
	v_and_b32_e32 v49, 0xffff0000, v216
	v_pk_fma_f32 v[48:49], v[32:33], s[14:15], v[48:49]
	v_lshlrev_b32_e32 v42, 16, v217
	v_cvt_pk_bf16_f32 v32, v48, v49
	v_fma_f32 v48, v48, v48, 0
	v_and_b32_e32 v43, 0xffff0000, v217
	v_fmac_f32_e32 v48, v49, v49
	v_pk_fma_f32 v[34:35], v[34:35], s[14:15], v[42:43]
	s_nop 0
	v_fmac_f32_e32 v48, v34, v34
	v_cvt_pk_bf16_f32 v33, v34, v35
	v_fmac_f32_e32 v48, v35, v35
	v_lshlrev_b32_e32 v34, 16, v218
	v_and_b32_e32 v35, 0xffff0000, v218
	v_pk_fma_f32 v[28:29], v[28:29], s[14:15], v[34:35]
	s_nop 0
	v_fmac_f32_e32 v48, v28, v28
	v_cvt_pk_bf16_f32 v34, v28, v29
	v_fmac_f32_e32 v48, v29, v29
	v_lshlrev_b32_e32 v28, 16, v219
	v_and_b32_e32 v29, 0xffff0000, v219
	v_pk_fma_f32 v[28:29], v[30:31], s[14:15], v[28:29]
	s_nop 0
	v_fmac_f32_e32 v48, v28, v28
	v_cvt_pk_bf16_f32 v35, v28, v29
	v_fmac_f32_e32 v48, v29, v29
	v_lshlrev_b32_e32 v28, 16, v212
	v_and_b32_e32 v29, 0xffff0000, v212
	v_pk_fma_f32 v[28:29], v[24:25], s[14:15], v[28:29]
	s_nop 0
	v_fmac_f32_e32 v48, v28, v28
	v_cvt_pk_bf16_f32 v24, v28, v29
	v_fmac_f32_e32 v48, v29, v29
	v_lshlrev_b32_e32 v28, 16, v213
	v_and_b32_e32 v29, 0xffff0000, v213
	v_pk_fma_f32 v[26:27], v[26:27], s[14:15], v[28:29]
	v_add_co_u32_e32 v28, vcc, s2, v144
	v_fmac_f32_e32 v48, v26, v26
	v_cvt_pk_bf16_f32 v25, v26, v27
	v_fmac_f32_e32 v48, v27, v27
	v_lshlrev_b32_e32 v26, 16, v214
	v_and_b32_e32 v27, 0xffff0000, v214
	v_pk_fma_f32 v[20:21], v[20:21], s[14:15], v[26:27]
	v_addc_co_u32_e32 v29, vcc, 0, v145, vcc
	v_fmac_f32_e32 v48, v20, v20
	v_cvt_pk_bf16_f32 v26, v20, v21
	v_fmac_f32_e32 v48, v21, v21
	v_lshlrev_b32_e32 v20, 16, v215
	v_and_b32_e32 v21, 0xffff0000, v215
	v_pk_fma_f32 v[20:21], v[22:23], s[14:15], v[20:21]
	s_nop 0
	v_fmac_f32_e32 v48, v20, v20
	v_fmac_f32_e32 v48, v21, v21
	v_cvt_pk_bf16_f32 v27, v20, v21
	ds_bpermute_b32 v20, v153, v48
	global_store_dwordx4 v[46:47], v[32:35], off offset:-2048
	global_store_dwordx4 v[46:47], v[24:27], off offset:2048
	s_waitcnt lgkmcnt(0)
	v_add_f32_e32 v30, v48, v20
	ds_bpermute_b32 v31, v152, v30
	s_waitcnt vmcnt(14)
	v_lshlrev_b32_e32 v32, 16, v224
	v_and_b32_e32 v33, 0xffff0000, v224
	v_pk_fma_f32 v[32:33], v[16:17], s[14:15], v[32:33]
	v_lshlrev_b32_e32 v24, 16, v225
	v_cvt_pk_bf16_f32 v16, v32, v33
	v_fma_f32 v32, v32, v32, 0
	v_and_b32_e32 v25, 0xffff0000, v225
	v_fmac_f32_e32 v32, v33, v33
	v_pk_fma_f32 v[18:19], v[18:19], s[14:15], v[24:25]
	s_nop 0
	v_fmac_f32_e32 v32, v18, v18
	v_cvt_pk_bf16_f32 v17, v18, v19
	v_fmac_f32_e32 v32, v19, v19
	v_lshlrev_b32_e32 v18, 16, v226
	v_and_b32_e32 v19, 0xffff0000, v226
	v_pk_fma_f32 v[12:13], v[12:13], s[14:15], v[18:19]
	s_nop 0
	v_fmac_f32_e32 v32, v12, v12
	v_cvt_pk_bf16_f32 v18, v12, v13
	v_fmac_f32_e32 v32, v13, v13
	v_lshlrev_b32_e32 v12, 16, v227
	v_and_b32_e32 v13, 0xffff0000, v227
	v_pk_fma_f32 v[12:13], v[14:15], s[14:15], v[12:13]
	s_nop 0
	v_fmac_f32_e32 v32, v12, v12
	v_cvt_pk_bf16_f32 v19, v12, v13
	v_fmac_f32_e32 v32, v13, v13
	v_lshlrev_b32_e32 v12, 16, v220
	v_and_b32_e32 v13, 0xffff0000, v220
	v_pk_fma_f32 v[12:13], v[8:9], s[14:15], v[12:13]
	s_nop 0
	v_fmac_f32_e32 v32, v12, v12
	v_cvt_pk_bf16_f32 v8, v12, v13
	v_fmac_f32_e32 v32, v13, v13
	v_lshlrev_b32_e32 v12, 16, v221
	v_and_b32_e32 v13, 0xffff0000, v221
	v_pk_fma_f32 v[10:11], v[10:11], s[14:15], v[12:13]
	s_nop 0
	v_fmac_f32_e32 v32, v10, v10
	v_cvt_pk_bf16_f32 v9, v10, v11
	v_fmac_f32_e32 v32, v11, v11
	v_lshlrev_b32_e32 v10, 16, v222
	v_and_b32_e32 v11, 0xffff0000, v222
	v_pk_fma_f32 v[4:5], v[4:5], s[14:15], v[10:11]
	s_nop 0
	v_fmac_f32_e32 v32, v4, v4
	v_cvt_pk_bf16_f32 v10, v4, v5
	v_fmac_f32_e32 v32, v5, v5
	v_lshlrev_b32_e32 v4, 16, v223
	v_and_b32_e32 v5, 0xffff0000, v223
	v_pk_fma_f32 v[4:5], v[6:7], s[14:15], v[4:5]
	s_nop 0
	v_fmac_f32_e32 v32, v4, v4
	v_fmac_f32_e32 v32, v5, v5
	v_cvt_pk_bf16_f32 v11, v4, v5
	ds_bpermute_b32 v4, v153, v32
	global_store_dwordx4 v[28:29], v[16:19], off offset:-2048
	global_store_dwordx4 v[28:29], v[8:11], off offset:2048
	s_waitcnt lgkmcnt(0)
	v_add_f32_e32 v4, v32, v4
	ds_bpermute_b32 v5, v152, v4
	s_and_saveexec_b64 s[2:3], s[38:39]
	v_add_f32_e32 v2, v30, v31
	v_add_f32_e32 v6, v52, v53
	v_add_f32_e32 v7, v94, v95
	v_cndmask_b32_e64 v2, v2, v6, s[42:43]
	v_cndmask_b32_e64 v2, v2, v7, s[40:41]
	s_or_b64 exec, exec, s[2:3]
	v_add_f32_e32 v8, v36, v37
	s_waitcnt lgkmcnt(0)
	v_add_f32_e32 v4, v4, v5
	v_add_f32_e32 v7, v68, v69
	v_cndmask_b32_e64 v4, v4, v8, s[42:43]
	v_add_f32_e32 v6, v100, v101
	v_cndmask_b32_e64 v4, v4, v7, s[40:41]
	v_cndmask_b32_e64 v6, v4, v6, s[36:37]
	v_add_u32_e32 v4, v148, v151
	v_ashrrev_i32_e32 v5, 31, v4
	v_readlane_b32 s2, v252, 45
	v_lshlrev_b64 v[4:5], 7, v[4:5]
	v_readlane_b32 s3, v252, 46
	s_and_b64 vcc, exec, s[44:45]
	s_nop 0
	v_lshl_add_u64 v[4:5], s[2:3], 0, v[4:5]
	s_lshl_b32 s2, s17, 2
	s_ashr_i32 s3, s2, 31
	v_lshl_add_u64 v[4:5], s[2:3], 2, v[4:5]
	v_readlane_b32 s2, v255, 9
	v_readlane_b32 s3, v255, 10
	s_nop 1
	v_lshl_add_u64 v[4:5], v[4:5], 0, s[2:3]
	s_mov_b64 s[2:3], -1
	global_store_dword v[4:5], v2, off
	global_store_dword v[4:5], v6, off offset:2048
	s_cbranch_vccnz .LBB0_820
	s_andn2_b64 vcc, exec, s[12:13]
	s_cbranch_vccnz .LBB0_819
	s_barrier
	s_branch .LBB0_819

.LBB0_965:
	v_readlane_b32 s2, v252, 21
	v_readlane_b32 s3, v252, 22
	s_cmp_lt_i32 s2, 38
	s_cselect_b64 s[0:1], -1, 0
	s_cmp_gt_i32 s3, 37
	s_cselect_b64 s[2:3], -1, 0
	s_and_b64 s[0:1], s[0:1], s[2:3]
	s_and_b64 vcc, exec, s[0:1]
	s_cbranch_vccz .LBB0_971
	v_readlane_b32 s0, v252, 4
	s_lshl_b32 s0, s0, 3
	v_readlane_b32 s1, v252, 42
	s_add_i32 s2, s0, s1
	s_cmpk_gt_i32 s2, 0x1fff
	s_cbranch_scc1 .LBB0_971
	v_readlane_b32 s4, v252, 5
	s_waitcnt vmcnt(0)
	v_and_b32_e32 v36, 63, v0
	v_readlane_b32 s10, v252, 11
	v_readlane_b32 s11, v252, 12
	v_readlane_b32 s14, v252, 15
	v_readlane_b32 s15, v252, 16
	v_lshlrev_b32_e32 v34, 4, v36
	v_mov_b32_e32 v35, 0
	s_mov_b64 s[10:11], s[14:15]
	v_lshl_add_u64 v[16:17], s[10:11], 0, v[34:35]
	v_add_co_u32_e32 v32, vcc, 0x1000, v16
	global_load_dwordx4 v[0:3], v34, s[10:11]
	global_load_dwordx4 v[4:7], v34, s[10:11] offset:1024
	global_load_dwordx4 v[8:11], v34, s[10:11] offset:2048
	global_load_dwordx4 v[12:15], v34, s[10:11] offset:3072
	v_addc_co_u32_e32 v33, vcc, 0, v17, vcc
	s_waitcnt lgkmcnt(0)
	global_load_dwordx4 v[16:19], v[32:33], off
	global_load_dwordx4 v[20:23], v[32:33], off offset:1024
	global_load_dwordx4 v[24:27], v[32:33], off offset:2048
	global_load_dwordx4 v[28:31], v[32:33], off offset:3072
	v_and_b32_e32 v32, 64, v208
	v_add_u32_e32 v32, 64, v32
	v_xor_b32_e32 v33, 1, v208
	v_cmp_lt_i32_e64 s[0:1], v33, v32
	s_ashr_i32 s3, s2, 31
	v_readlane_b32 s28, v254, 61
	v_cndmask_b32_e64 v33, v208, v33, s[0:1]
	v_lshlrev_b32_e32 v38, 2, v33
	v_xor_b32_e32 v33, 2, v208
	v_cmp_lt_i32_e64 s[0:1], v33, v32
	v_readlane_b32 s29, v254, 62
	v_readlane_b32 s5, v252, 6
	v_cndmask_b32_e64 v33, v208, v33, s[0:1]
	v_lshlrev_b32_e32 v39, 2, v33
	v_xor_b32_e32 v33, 4, v208
	v_cmp_lt_i32_e64 s[0:1], v33, v32
	v_readlane_b32 s12, v252, 13
	v_readlane_b32 s13, v252, 14
	v_cndmask_b32_e64 v33, v208, v33, s[0:1]
	v_lshlrev_b32_e32 v40, 2, v33
	v_xor_b32_e32 v33, 8, v208
	v_cmp_lt_i32_e64 s[0:1], v33, v32
	v_readlane_b32 s16, v252, 17
	v_readlane_b32 s17, v252, 18
	v_cndmask_b32_e64 v33, v208, v33, s[0:1]
	v_lshlrev_b32_e32 v41, 2, v33
	v_xor_b32_e32 v33, 16, v208
	v_cmp_lt_i32_e64 s[0:1], v33, v32
	s_ashr_i32 s29, s28, 31
	v_readlane_b32 s18, v252, 19
	v_cndmask_b32_e64 v33, v208, v33, s[0:1]
	v_lshlrev_b32_e32 v42, 2, v33
	v_xor_b32_e32 v33, 32, v208
	v_cmp_lt_i32_e64 s[0:1], v33, v32
	v_readlane_b32 s19, v252, 20
	s_mov_b64 s[12:13], s[16:17]
	v_cndmask_b32_e64 v32, v208, v33, s[0:1]
	v_lshlrev_b32_e32 v43, 2, v32
	s_lshl_b64 s[0:1], s[2:3], 7
	v_lshlrev_b32_e32 v32, 2, v36
	v_mov_b32_e32 v33, v35
	v_lshl_add_u64 v[32:33], s[0:1], 0, v[32:33]
	s_mov_b64 s[0:1], 0x100000
	v_lshl_add_u64 v[32:33], v[32:33], 0, s[0:1]
	s_lshl_b64 s[4:5], s[28:29], 7
	s_lshl_b64 s[0:1], s[2:3], 13
	s_add_u32 s0, s12, s0
	s_addc_u32 s1, s13, s1
	v_lshl_add_u64 v[34:35], s[0:1], 0, v[34:35]
	s_mov_b64 s[0:1], 0x1000
	v_readlane_b32 s6, v252, 7
	v_readlane_b32 s7, v252, 8
	v_readlane_b32 s8, v252, 9
	v_readlane_b32 s9, v252, 10
	v_lshl_add_u64 v[34:35], v[34:35], 0, s[0:1]
	s_lshl_b64 s[0:1], s[2:3], 12
	v_cmp_gt_u32_e32 vcc, 32, v36
	s_lshl_b64 s[6:7], s[28:29], 13
	v_lshl_or_b32 v36, v36, 3, s0
	v_mov_b32_e32 v37, s1
	s_lshl_b64 s[8:9], s[28:29], 12
	v_mov_b32_e32 v44, 0x358637bd
	s_mov_b32 s3, 0x4200000
	s_mov_b64 s[14:15], s[18:19]
	v_lshrrev_b32_e32 v76, 3, v208
	v_lshlrev_b32_e32 v76, 10, v76
	v_and_b32_e32 v77, 7, v208
	v_lshl_or_b32 v76, v77, 3, v76
	s_branch .LBB0_969
.LBB0_968:
	s_or_b64 exec, exec, s[0:1]
	v_readlane_b32 s12, v252, 5
	v_readlane_b32 s26, v252, 19
	v_readlane_b32 s27, v252, 20
	s_waitcnt vmcnt(0)
	ds_bpermute_b32 v48, v38, v45
	s_add_i32 s2, s2, s28
	s_sub_i32 s98, s2, s28
	s_lshr_b32 s99, s98, 4
	s_lshl_b32 s99, s99, 16
	s_and_b32 s100, s98, 15
	s_lshl_b32 s100, s100, 6
	s_add_u32 s99, s99, s100
	s_add_u32 s99, s99, s3
	s_lshl_b32 s100, s98, 2
	s_and_b32 s100, s100, 32
	s_add_u32 s98, s26, s99
	s_addc_u32 s99, s27, 0
	v_xor_b32_e32 v77, s100, v76
	v_add_u32_e32 v78, 0x2000, v77
	v_add_u32_e32 v79, 0x4000, v77
	v_add_u32_e32 v80, 0x6000, v77
	v_add_u32_e32 v81, 0x8000, v77
	v_add_u32_e32 v82, 0xa000, v77
	v_add_u32_e32 v83, 0xc000, v77
	v_add_u32_e32 v84, 0xe000, v77
	s_waitcnt lgkmcnt(0)
	v_add_f32_e32 v45, v45, v48
	global_load_dwordx2 v[46:47], v77, s[98:99]
	global_load_dwordx2 v[60:61], v78, s[98:99]
	global_load_dwordx2 v[62:63], v79, s[98:99]
	global_load_dwordx2 v[64:65], v80, s[98:99]
	global_load_dwordx2 v[66:67], v81, s[98:99]
	global_load_dwordx2 v[68:69], v82, s[98:99]
	global_load_dwordx2 v[70:71], v83, s[98:99]
	global_load_dwordx2 v[72:73], v84, s[98:99]
	ds_bpermute_b32 v48, v39, v45
	v_lshl_add_u64 v[32:33], v[32:33], 0, s[4:5]
	s_cmpk_lt_i32 s2, 0x2000
	v_lshl_add_u64 v[36:37], v[36:37], 0, s[8:9]
	v_readlane_b32 s13, v252, 6
	s_waitcnt lgkmcnt(0)
	v_add_f32_e32 v45, v45, v48
	ds_bpermute_b32 v48, v40, v45
	v_readlane_b32 s14, v252, 7
	v_readlane_b32 s15, v252, 8
	v_readlane_b32 s16, v252, 9
	v_readlane_b32 s17, v252, 10
	s_waitcnt lgkmcnt(0)
	v_add_f32_e32 v45, v45, v48
	ds_bpermute_b32 v48, v41, v45
	v_readlane_b32 s18, v252, 11
	v_readlane_b32 s19, v252, 12
	v_readlane_b32 s20, v252, 13
	v_readlane_b32 s21, v252, 14
	s_waitcnt lgkmcnt(0)
	v_add_f32_e32 v45, v45, v48
	ds_bpermute_b32 v48, v42, v45
	v_readlane_b32 s22, v252, 15
	v_readlane_b32 s23, v252, 16
	v_readlane_b32 s24, v252, 17
	v_readlane_b32 s25, v252, 18
	s_waitcnt lgkmcnt(0)
	v_add_f32_e32 v45, v45, v48
	ds_bpermute_b32 v48, v43, v45
	s_waitcnt lgkmcnt(0)
	v_add_f32_e32 v45, v45, v48
	v_fmamk_f32 v45, v45, 0x3a000000, v44
	v_rsq_f32_e32 v52, v45
	s_waitcnt vmcnt(7)
	v_lshlrev_b32_e32 v48, 16, v46
	v_and_b32_e32 v49, 0xffff0000, v46
	v_lshlrev_b32_e32 v46, 16, v47
	v_and_b32_e32 v47, 0xffff0000, v47
	v_pk_mul_f32 v[54:55], v[52:53], v[48:49] op_sel_hi:[0,1]
	v_pk_mul_f32 v[46:47], v[52:53], v[46:47] op_sel_hi:[0,1]
	v_pk_mul_f32 v[48:49], v[2:3], v[46:47]
	v_pk_mul_f32 v[46:47], v[0:1], v[54:55]
	global_store_dwordx4 v[34:35], v[46:49], off offset:-4096
	s_nop 1
	s_waitcnt vmcnt(7)
	v_lshlrev_b32_e32 v48, 16, v60
	v_and_b32_e32 v49, 0xffff0000, v60
	v_lshlrev_b32_e32 v46, 16, v61
	v_and_b32_e32 v47, 0xffff0000, v61
	v_pk_mul_f32 v[54:55], v[52:53], v[48:49] op_sel_hi:[0, 1]
	v_pk_mul_f32 v[46:47], v[52:53], v[46:47] op_sel_hi:[0, 1]
	v_pk_mul_f32 v[48:49], v[6:7], v[46:47]
	v_pk_mul_f32 v[46:47], v[4:5], v[54:55]
	global_store_dwordx4 v[34:35], v[46:49], off offset:-3072
	s_nop 1
	s_waitcnt vmcnt(7)
	v_lshlrev_b32_e32 v48, 16, v62
	v_and_b32_e32 v49, 0xffff0000, v62
	v_lshlrev_b32_e32 v46, 16, v63
	v_and_b32_e32 v47, 0xffff0000, v63
	v_pk_mul_f32 v[54:55], v[52:53], v[48:49] op_sel_hi:[0, 1]
	v_pk_mul_f32 v[46:47], v[52:53], v[46:47] op_sel_hi:[0, 1]
	v_pk_mul_f32 v[48:49], v[10:11], v[46:47]
	v_pk_mul_f32 v[46:47], v[8:9], v[54:55]
	global_store_dwordx4 v[34:35], v[46:49], off offset:-2048
	s_nop 1
	s_waitcnt vmcnt(7)
	v_lshlrev_b32_e32 v48, 16, v64
	v_and_b32_e32 v49, 0xffff0000, v64
	v_lshlrev_b32_e32 v46, 16, v65
	v_and_b32_e32 v47, 0xffff0000, v65
	v_pk_mul_f32 v[54:55], v[52:53], v[48:49] op_sel_hi:[0, 1]
	v_pk_mul_f32 v[46:47], v[52:53], v[46:47] op_sel_hi:[0, 1]
	v_pk_mul_f32 v[48:49], v[14:15], v[46:47]
	v_pk_mul_f32 v[46:47], v[12:13], v[54:55]
	global_store_dwordx4 v[34:35], v[46:49], off offset:-1024
	s_nop 1
	s_waitcnt vmcnt(7)
	v_lshlrev_b32_e32 v48, 16, v66
	v_and_b32_e32 v49, 0xffff0000, v66
	v_lshlrev_b32_e32 v46, 16, v67
	v_and_b32_e32 v47, 0xffff0000, v67
	v_pk_mul_f32 v[54:55], v[52:53], v[48:49] op_sel_hi:[0, 1]
	v_pk_mul_f32 v[46:47], v[52:53], v[46:47] op_sel_hi:[0, 1]
	v_pk_mul_f32 v[48:49], v[18:19], v[46:47]
	v_pk_mul_f32 v[46:47], v[16:17], v[54:55]
	global_store_dwordx4 v[34:35], v[46:49], off
	s_nop 1
	s_waitcnt vmcnt(7)
	v_lshlrev_b32_e32 v48, 16, v68
	v_and_b32_e32 v49, 0xffff0000, v68
	v_lshlrev_b32_e32 v46, 16, v69
	v_and_b32_e32 v47, 0xffff0000, v69
	v_pk_mul_f32 v[54:55], v[52:53], v[48:49] op_sel_hi:[0, 1]
	v_pk_mul_f32 v[46:47], v[52:53], v[46:47] op_sel_hi:[0, 1]
	v_pk_mul_f32 v[48:49], v[22:23], v[46:47]
	v_pk_mul_f32 v[46:47], v[20:21], v[54:55]
	global_store_dwordx4 v[34:35], v[46:49], off offset:1024
	s_nop 1
	s_waitcnt vmcnt(7)
	v_lshlrev_b32_e32 v48, 16, v70
	v_and_b32_e32 v49, 0xffff0000, v70
	v_lshlrev_b32_e32 v46, 16, v71
	v_and_b32_e32 v47, 0xffff0000, v71
	v_pk_mul_f32 v[54:55], v[52:53], v[48:49] op_sel_hi:[0, 1]
	v_pk_mul_f32 v[46:47], v[52:53], v[46:47] op_sel_hi:[0, 1]
	v_pk_mul_f32 v[48:49], v[26:27], v[46:47]
	v_pk_mul_f32 v[46:47], v[24:25], v[54:55]
	global_store_dwordx4 v[34:35], v[46:49], off offset:2048
	s_nop 1
	s_waitcnt vmcnt(7)
	v_lshlrev_b32_e32 v48, 16, v72
	v_and_b32_e32 v49, 0xffff0000, v72
	v_lshlrev_b32_e32 v46, 16, v73
	v_and_b32_e32 v47, 0xffff0000, v73
	v_pk_mul_f32 v[50:51], v[52:53], v[48:49] op_sel_hi:[0, 1]
	v_pk_mul_f32 v[46:47], v[52:53], v[46:47] op_sel_hi:[0, 1]
	v_pk_mul_f32 v[48:49], v[30:31], v[46:47]
	v_pk_mul_f32 v[46:47], v[28:29], v[50:51]
	global_store_dwordx4 v[34:35], v[46:49], off offset:3072
	v_lshl_add_u64 v[34:35], v[34:35], 0, s[6:7]
	s_cbranch_scc0 .LBB0_971
